# v070 + dead exit test (compare + never-taken branch) removed from the peeled first K-iteration of the fixed-length GEMM loops (G1, GLU, PR0, PR1)
# baseline (speedup 1.0000x reference)
; #define PG8_STAGE(bufoff, gbase, voff) do { _Pragma("unroll") for (int _i = 0; _i < 2; ++_i) \
;         __builtin_amdgcn_global_load_lds((const unsigned*)((const char*)(gbase) + (voff)[_i]), (PG8_LAS unsigned*)(lds + (bufoff) + ldsw + _i * 8192), 16, 0, AUX_A); } while (0)
; #define PG8_STAGEB(bufoff, gbase, voff) do { _Pragma("unroll") for (int _i = 0; _i < 2; ++_i) \
;         __builtin_amdgcn_global_load_lds((const unsigned*)((const char*)(gbase) + (voff)[_i]), (PG8_LAS unsigned*)(lds + (bufoff) + ldsw + _i * 8192), 16, 0, AUX_B); } while (0)
; #define PG8_LDA(dst, b, h) do { _Pragma("unroll") for (int m = 0; m < 4; ++m) _Pragma("unroll") for (int k = 0; k < 2; ++k) dst[m][k] = *(const PG8_LAS bf16x8*)(lds + PG8_SA(b, h) + aoff + m * 2048 + k * 1024); } while (0)
; #define PG8_LDB(dst, b, h) do { _Pragma("unroll") for (int n = 0; n < 2; ++n) _Pragma("unroll") for (int k = 0; k < 2; ++k) dst[n][k] = *(const PG8_LAS bf16x8*)(lds + PG8_SB(b, h) + boff + n * 2048 + k * 1024); } while (0)
; #define PG8_WAIT_V(n) asm volatile("s_waitcnt vmcnt(" #n ")" ::: "memory")
; #define PG8_WAIT_L(n) asm volatile("s_waitcnt lgkmcnt(" #n ")" ::: "memory")
; #define PG8_BAR __builtin_amdgcn_s_barrier()
; template <class Epi, class Sched, bool ALIGN_EPI = false, bool SP2 = false>
; __device__ __forceinline__ void gemm_phase(PG8_LAS unsigned char* lds, const Gemm g, const Sched& S, const Epi& E) {
;     ...
;         for (int t = 0; t < nt; t += 2) {
;             const bool last = (t == nt - 2);
;             const char* a1 = PG8_KP(cA, t + 1, rot, nt);
;             const char* a2 = last ? nAr : PG8_KP(cA, t + 2, rot, nt); const char* b2 = last ? nBr : PG8_KP(cB, t + 2, rot, nt);
;             const char* a3 = a2 + kstep; const char* b3 = b2 + kstep;
;             if (last && has_next) S.a_ready(nxt);
;             if constexpr (SP2) {
;             PG8_LDB(B0, 0, 0); PG8_LDB(B1, 0, 1); PG8_SCHED; PG8_LDA(At, 0, 0); PG8_STAGE(PG8_SA(1, 1), a1 + hstep, voffA);
;             PG8_WAIT_V(8); PG8_WAIT_L(0); PG8_BAR; PG8_MMA(0, 0, At, B0); PG8_MMA(0, 1, At, B1); PG8_BAR; PG8_SCHED;
;             PG8_LDA(At, 0, 1); PG8_STAGEB(PG8_SB(0, 0), b2, voffB); PG8_STAGEB(PG8_SB(0, 1), b2 + hstep, voffB); PG8_STAGE(PG8_SA(0, 0), a2, voffA);
;             PG8_WAIT_V(8); PG8_WAIT_L(0); PG8_BAR; PG8_MMA(1, 0, At, B0); PG8_MMA(1, 1, At, B1); PG8_BAR; PG8_SCHED;
.Lrp_270:
.Lpk_270:
	s_add_i32 s81, s29, 2
	s_cmp_lt_u32 s29, 30
	s_cselect_b32 s0, 0, 0xffffffe0
	s_add_i32 s0, s81, s0
	s_ashr_i32 s1, s0, 31
	s_lshl_b64 s[0:1], s[0:1], 7
	s_add_u32 s42, s40, s0
	s_addc_u32 s43, s41, s1
	s_add_u32 s0, s38, s0
	s_addc_u32 s1, s39, s1
	s_cmp_eq_u32 s29, 30
	s_cselect_b32 s59, s49, s43
	s_cselect_b32 s58, s51, s42
	s_cselect_b32 s61, vcc_lo, s1
	s_cselect_b32 s60, vcc_hi, s0
	s_add_i32 s43, 0, 0x10000
	s_add_i32 s97, s43, s70
	s_add_i32 s46, 0, 0x14000
	s_add_i32 m0, s96, 0xc000
	s_add_i32 s69, s96, 0xe000
	s_add_i32 s84, s97, 0x2000
	s_add_u32 s62, s60, 0x80000
	s_addc_u32 s63, s61, 0
	s_add_i32 s4, s46, s70
	s_add_i32 s5, s4, 0x2000
	s_add_i32 s1, 0, 0x18000
	s_add_i32 s47, 0, 0x1c000
	s_add_u32 s56, s58, 0x80000
	s_addc_u32 s57, s59, 0
	s_add_i32 s0, s1, s70
	s_add_i32 s89, s0, 0x2000
	s_add_u32 s42, s60, 0x80080
	s_addc_u32 s43, s61, 0
	s_add_i32 s46, s47, s70
	s_add_i32 s92, s46, 0x2000
	global_load_lds_dwordx4 v[134:135], off
	s_mov_b32 m0, s69
	s_nop 0
	global_load_lds_dwordx4 v[132:133], off
	s_waitcnt vmcnt(8)
	s_waitcnt lgkmcnt(0)
	s_setprio 1
	s_barrier
	v_mfma_f32_16x16x32_bf16 v[128:131], v[136:139], v[192:195], 0
	v_mfma_f32_16x16x32_bf16 v[128:131], v[140:143], v[196:199], v[128:131]
	v_mfma_f32_16x16x32_bf16 v[124:127], v[144:147], v[192:195], 0
	v_mfma_f32_16x16x32_bf16 v[124:127], v[148:151], v[196:199], v[124:127]
	v_mfma_f32_16x16x32_bf16 v[112:115], v[136:139], v[200:203], 0
	v_mfma_f32_16x16x32_bf16 v[112:115], v[140:143], v[224:227], v[112:115]
	v_mfma_f32_16x16x32_bf16 v[108:111], v[144:147], v[200:203], 0
	v_mfma_f32_16x16x32_bf16 v[108:111], v[148:151], v[224:227], v[108:111]
	v_mfma_f32_16x16x32_bf16 v[94:97], v[136:139], v[228:231], 0
	v_mfma_f32_16x16x32_bf16 v[94:97], v[140:143], v[232:235], v[94:97]
	v_mfma_f32_16x16x32_bf16 v[90:93], v[144:147], v[228:231], 0
	v_mfma_f32_16x16x32_bf16 v[90:93], v[148:151], v[232:235], v[90:93]
	v_mfma_f32_16x16x32_bf16 v[78:81], v[136:139], v[236:239], 0
	v_mfma_f32_16x16x32_bf16 v[78:81], v[140:143], v[240:243], v[78:81]
	v_mfma_f32_16x16x32_bf16 v[74:77], v[144:147], v[236:239], 0
	v_mfma_f32_16x16x32_bf16 v[74:77], v[148:151], v[240:243], v[74:77]
	s_setprio 0
	s_setprio 1
	v_mfma_f32_16x16x32_bf16 v[120:123], v[152:155], v[192:195], 0
	v_mfma_f32_16x16x32_bf16 v[120:123], v[156:159], v[196:199], v[120:123]
	v_mfma_f32_16x16x32_bf16 v[116:119], v[160:163], v[192:195], 0
	v_mfma_f32_16x16x32_bf16 v[116:119], v[164:167], v[196:199], v[116:119]
	v_mfma_f32_16x16x32_bf16 v[104:107], v[152:155], v[200:203], 0
	v_mfma_f32_16x16x32_bf16 v[104:107], v[156:159], v[224:227], v[104:107]
	v_mfma_f32_16x16x32_bf16 v[100:103], v[160:163], v[200:203], 0
	v_mfma_f32_16x16x32_bf16 v[100:103], v[164:167], v[224:227], v[100:103]
	v_mfma_f32_16x16x32_bf16 v[86:89], v[152:155], v[228:231], 0
	v_mfma_f32_16x16x32_bf16 v[86:89], v[156:159], v[232:235], v[86:89]
	v_mfma_f32_16x16x32_bf16 v[82:85], v[160:163], v[228:231], 0
	v_mfma_f32_16x16x32_bf16 v[82:85], v[164:167], v[232:235], v[82:85]
	v_mfma_f32_16x16x32_bf16 v[70:73], v[152:155], v[236:239], 0
	v_mfma_f32_16x16x32_bf16 v[70:73], v[156:159], v[240:243], v[70:73]
	s_setprio 2
	s_barrier
	v_mfma_f32_16x16x32_bf16 v[66:69], v[160:163], v[236:239], 0
	v_mfma_f32_16x16x32_bf16 v[66:69], v[164:167], v[240:243], v[66:69]
	s_setprio 0
	s_mov_b32 m0, s97
	v_lshl_add_u64 v[244:245], s[60:61], 0, v[184:185]
	ds_read_b128 v[192:195], v222 offset:16384
	ds_read_b128 v[196:199], v222 offset:17408
	ds_read_b128 v[200:203], v222 offset:18432
	ds_read_b128 v[224:227], v222 offset:19456
	ds_read_b128 v[228:231], v222 offset:20480
	ds_read_b128 v[232:235], v222 offset:21504
	ds_read_b128 v[236:239], v222 offset:22528
	ds_read_b128 v[240:243], v222 offset:23552
	global_load_lds_dwordx4 v[244:245], off
	v_lshl_add_u64 v[246:247], s[60:61], 0, v[180:181]
	s_mov_b32 m0, s84
	v_lshl_add_u64 v[212:213], s[62:63], 0, v[184:185]
	global_load_lds_dwordx4 v[246:247], off
	s_mov_b32 m0, s4
	v_lshl_add_u64 v[172:173], s[58:59], 0, v[182:183]
	global_load_lds_dwordx4 v[212:213], off
	v_lshl_add_u64 v[212:213], s[62:63], 0, v[180:181]
	s_mov_b32 m0, s5
	s_nop 0
	global_load_lds_dwordx4 v[212:213], off
	v_lshl_add_u64 v[212:213], s[58:59], 0, v[186:187]
	s_mov_b32 m0, s96
	s_nop 0
	global_load_lds_dwordx4 v[212:213], off
	s_mov_b32 m0, s71
	s_nop 0
	global_load_lds_dwordx4 v[172:173], off
	s_waitcnt vmcnt(8)
	s_waitcnt lgkmcnt(0)
	s_setprio 1
	s_barrier
	v_mfma_f32_16x16x32_bf16 v[62:65], v[136:139], v[192:195], 0
	v_mfma_f32_16x16x32_bf16 v[62:65], v[140:143], v[196:199], v[62:65]
	v_mfma_f32_16x16x32_bf16 v[58:61], v[144:147], v[192:195], 0
	v_mfma_f32_16x16x32_bf16 v[58:61], v[148:151], v[196:199], v[58:61]
	v_mfma_f32_16x16x32_bf16 v[46:49], v[136:139], v[200:203], 0
	v_mfma_f32_16x16x32_bf16 v[46:49], v[140:143], v[224:227], v[46:49]
	v_mfma_f32_16x16x32_bf16 v[42:45], v[144:147], v[200:203], 0
	v_mfma_f32_16x16x32_bf16 v[42:45], v[148:151], v[224:227], v[42:45]
	v_mfma_f32_16x16x32_bf16 v[30:33], v[136:139], v[228:231], 0
	v_mfma_f32_16x16x32_bf16 v[30:33], v[140:143], v[232:235], v[30:33]
	v_mfma_f32_16x16x32_bf16 v[26:29], v[144:147], v[228:231], 0
	v_mfma_f32_16x16x32_bf16 v[26:29], v[148:151], v[232:235], v[26:29]
	v_mfma_f32_16x16x32_bf16 v[14:17], v[136:139], v[236:239], 0
	v_mfma_f32_16x16x32_bf16 v[14:17], v[140:143], v[240:243], v[14:17]
	v_mfma_f32_16x16x32_bf16 v[10:13], v[144:147], v[236:239], 0
	v_mfma_f32_16x16x32_bf16 v[10:13], v[148:151], v[240:243], v[10:13]
	s_setprio 0
	s_setprio 1
	v_mfma_f32_16x16x32_bf16 v[54:57], v[152:155], v[192:195], 0
	v_mfma_f32_16x16x32_bf16 v[54:57], v[156:159], v[196:199], v[54:57]
	v_mfma_f32_16x16x32_bf16 v[50:53], v[160:163], v[192:195], 0
	v_mfma_f32_16x16x32_bf16 v[50:53], v[164:167], v[196:199], v[50:53]
	v_mfma_f32_16x16x32_bf16 v[38:41], v[152:155], v[200:203], 0
	v_mfma_f32_16x16x32_bf16 v[38:41], v[156:159], v[224:227], v[38:41]
	v_mfma_f32_16x16x32_bf16 v[34:37], v[160:163], v[200:203], 0
	v_mfma_f32_16x16x32_bf16 v[34:37], v[164:167], v[224:227], v[34:37]
	v_mfma_f32_16x16x32_bf16 v[22:25], v[152:155], v[228:231], 0
	v_mfma_f32_16x16x32_bf16 v[22:25], v[156:159], v[232:235], v[22:25]
	v_mfma_f32_16x16x32_bf16 v[18:21], v[160:163], v[228:231], 0
	v_mfma_f32_16x16x32_bf16 v[18:21], v[164:167], v[232:235], v[18:21]
	v_mfma_f32_16x16x32_bf16 v[6:9], v[152:155], v[236:239], 0
	v_mfma_f32_16x16x32_bf16 v[6:9], v[156:159], v[240:243], v[6:9]
	s_setprio 2
	s_barrier
; #define PG8_STAGE(bufoff, gbase, voff) do { _Pragma("unroll") for (int _i = 0; _i < 2; ++_i) \
;         __builtin_amdgcn_global_load_lds((const unsigned*)((const char*)(gbase) + (voff)[_i]), (PG8_LAS unsigned*)(lds + (bufoff) + ldsw + _i * 8192), 16, 0, AUX_A); } while (0)
; #define PG8_STAGEB(bufoff, gbase, voff) do { _Pragma("unroll") for (int _i = 0; _i < 2; ++_i) \
;         __builtin_amdgcn_global_load_lds((const unsigned*)((const char*)(gbase) + (voff)[_i]), (PG8_LAS unsigned*)(lds + (bufoff) + ldsw + _i * 8192), 16, 0, AUX_B); } while (0)
; #define PG8_LDA(dst, b, h) do { _Pragma("unroll") for (int m = 0; m < 4; ++m) _Pragma("unroll") for (int k = 0; k < 2; ++k) dst[m][k] = *(const PG8_LAS bf16x8*)(lds + PG8_SA(b, h) + aoff + m * 2048 + k * 1024); } while (0)
; #define PG8_LDB(dst, b, h) do { _Pragma("unroll") for (int n = 0; n < 2; ++n) _Pragma("unroll") for (int k = 0; k < 2; ++k) dst[n][k] = *(const PG8_LAS bf16x8*)(lds + PG8_SB(b, h) + boff + n * 2048 + k * 1024); } while (0)
; #define PG8_MMA(ai, bj, At, Bt) do { __builtin_amdgcn_s_setprio(1); _Pragma("unroll") for (int m = 0; m < 4; ++m) _Pragma("unroll") for (int n = 0; n < 2; ++n) _Pragma("unroll") for (int k = 0; k < 2; ++k) \
;         acc[ai][bj][m][n] = __builtin_amdgcn_mfma_f32_16x16x32_bf16(Bt[n][k], At[m][k], acc[ai][bj][m][n], 0, 0, 0); __builtin_amdgcn_s_setprio(0); } while (0)
; #define PG8_WAIT_V(n) asm volatile("s_waitcnt vmcnt(" #n ")" ::: "memory")
; #define PG8_WAIT_L(n) asm volatile("s_waitcnt lgkmcnt(" #n ")" ::: "memory")
; #define PG8_BAR __builtin_amdgcn_s_barrier()
; #define PG8_SCHED __builtin_amdgcn_sched_barrier(0)
; template <class Epi, class Sched, bool ALIGN_EPI = false, bool SP2 = false>
; __device__ __forceinline__ void gemm_phase(PG8_LAS unsigned char* lds, const Gemm g, const Sched& S, const Epi& E) {
;     ...
;         for (int t = 0; t < nt; t += 2) {
;     ...
;             PG8_LDB(B0, 1, 0); PG8_LDB(B1, 1, 1); PG8_SCHED; PG8_LDA(At, 1, 0); PG8_STAGE(PG8_SA(0, 1), a2 + hstep, voffA);
;             PG8_WAIT_V(8); PG8_WAIT_L(0); PG8_BAR; PG8_MMA(0, 0, At, B0); PG8_MMA(0, 1, At, B1); PG8_BAR; PG8_SCHED;
;             PG8_LDA(At, 1, 1); PG8_STAGEB(PG8_SB(1, 0), b3, voffB); PG8_STAGEB(PG8_SB(1, 1), b3 + hstep, voffB); PG8_STAGE(PG8_SA(1, 0), a3, voffA);
;             PG8_WAIT_V(8); PG8_WAIT_L(0); PG8_BAR; PG8_MMA(1, 0, At, B0); PG8_MMA(1, 1, At, B1); PG8_BAR; PG8_SCHED;
	v_mfma_f32_16x16x32_bf16 v[2:5], v[160:163], v[236:239], 0
	v_mfma_f32_16x16x32_bf16 v[2:5], v[164:167], v[240:243], v[2:5]
	s_setprio 0
	v_add_u32_e32 v148, s1, v221
	v_add_u32_e32 v164, s47, v221
	ds_read_b128 v[136:139], v148
	ds_read_b128 v[140:143], v148 offset:1024
	ds_read_b128 v[144:147], v148 offset:2048
	ds_read_b128 v[148:151], v148 offset:3072
	ds_read_b128 v[152:155], v164
	ds_read_b128 v[156:159], v164 offset:1024
	ds_read_b128 v[160:163], v164 offset:2048
	ds_read_b128 v[164:167], v164 offset:3072
	s_mov_b32 m0, s33
	v_lshl_add_u64 v[168:169], s[56:57], 0, v[186:187]
	ds_read_b128 v[192:195], v222 offset:32768
	ds_read_b128 v[196:199], v222 offset:33792
	ds_read_b128 v[200:203], v222 offset:34816
	ds_read_b128 v[224:227], v222 offset:35840
	ds_read_b128 v[228:231], v222 offset:36864
	ds_read_b128 v[232:235], v222 offset:37888
	ds_read_b128 v[236:239], v222 offset:38912
	ds_read_b128 v[240:243], v222 offset:39936
	global_load_lds_dwordx4 v[168:169], off
	v_lshl_add_u64 v[168:169], s[56:57], 0, v[182:183]
	s_mov_b32 m0, s30
	s_nop 0
	global_load_lds_dwordx4 v[168:169], off
	s_waitcnt vmcnt(8)
	s_waitcnt lgkmcnt(0)
	s_setprio 1
	s_barrier
	v_mfma_f32_16x16x32_bf16 v[128:131], v[136:139], v[192:195], v[128:131]
	v_mfma_f32_16x16x32_bf16 v[128:131], v[140:143], v[196:199], v[128:131]
	v_mfma_f32_16x16x32_bf16 v[124:127], v[144:147], v[192:195], v[124:127]
	v_mfma_f32_16x16x32_bf16 v[124:127], v[148:151], v[196:199], v[124:127]
	v_mfma_f32_16x16x32_bf16 v[112:115], v[136:139], v[200:203], v[112:115]
	v_mfma_f32_16x16x32_bf16 v[112:115], v[140:143], v[224:227], v[112:115]
	v_mfma_f32_16x16x32_bf16 v[108:111], v[144:147], v[200:203], v[108:111]
	v_mfma_f32_16x16x32_bf16 v[108:111], v[148:151], v[224:227], v[108:111]
	v_mfma_f32_16x16x32_bf16 v[94:97], v[136:139], v[228:231], v[94:97]
	v_mfma_f32_16x16x32_bf16 v[94:97], v[140:143], v[232:235], v[94:97]
	v_mfma_f32_16x16x32_bf16 v[90:93], v[144:147], v[228:231], v[90:93]
	v_mfma_f32_16x16x32_bf16 v[90:93], v[148:151], v[232:235], v[90:93]
	v_mfma_f32_16x16x32_bf16 v[78:81], v[136:139], v[236:239], v[78:81]
	v_mfma_f32_16x16x32_bf16 v[78:81], v[140:143], v[240:243], v[78:81]
	v_mfma_f32_16x16x32_bf16 v[74:77], v[144:147], v[236:239], v[74:77]
	v_mfma_f32_16x16x32_bf16 v[74:77], v[148:151], v[240:243], v[74:77]
	s_setprio 0
	s_setprio 1
	v_mfma_f32_16x16x32_bf16 v[120:123], v[152:155], v[192:195], v[120:123]
	v_mfma_f32_16x16x32_bf16 v[120:123], v[156:159], v[196:199], v[120:123]
	v_mfma_f32_16x16x32_bf16 v[116:119], v[160:163], v[192:195], v[116:119]
	v_mfma_f32_16x16x32_bf16 v[116:119], v[164:167], v[196:199], v[116:119]
	v_mfma_f32_16x16x32_bf16 v[104:107], v[152:155], v[200:203], v[104:107]
	v_mfma_f32_16x16x32_bf16 v[104:107], v[156:159], v[224:227], v[104:107]
	v_mfma_f32_16x16x32_bf16 v[100:103], v[160:163], v[200:203], v[100:103]
	v_mfma_f32_16x16x32_bf16 v[100:103], v[164:167], v[224:227], v[100:103]
	v_mfma_f32_16x16x32_bf16 v[86:89], v[152:155], v[228:231], v[86:89]
	v_mfma_f32_16x16x32_bf16 v[86:89], v[156:159], v[232:235], v[86:89]
	v_mfma_f32_16x16x32_bf16 v[82:85], v[160:163], v[228:231], v[82:85]
	v_mfma_f32_16x16x32_bf16 v[82:85], v[164:167], v[232:235], v[82:85]
	v_mfma_f32_16x16x32_bf16 v[70:73], v[152:155], v[236:239], v[70:73]
	v_mfma_f32_16x16x32_bf16 v[70:73], v[156:159], v[240:243], v[70:73]
	s_setprio 2
	s_barrier
	v_mfma_f32_16x16x32_bf16 v[66:69], v[160:163], v[236:239], v[66:69]
	v_mfma_f32_16x16x32_bf16 v[66:69], v[164:167], v[240:243], v[66:69]
	s_setprio 0
	s_mov_b32 m0, s0
	v_lshl_add_u64 v[168:169], v[244:245], 0, s[76:77]
	ds_read_b128 v[192:195], v222 offset:49152
	ds_read_b128 v[196:199], v222 offset:50176
	ds_read_b128 v[200:203], v222 offset:51200
	ds_read_b128 v[224:227], v222 offset:52224
	ds_read_b128 v[228:231], v222 offset:53248
	ds_read_b128 v[232:235], v222 offset:54272
	ds_read_b128 v[236:239], v222 offset:55296
	ds_read_b128 v[240:243], v222 offset:56320
	global_load_lds_dwordx4 v[168:169], off
	v_lshl_add_u64 v[168:169], v[246:247], 0, s[76:77]
	s_mov_b32 m0, s89
	s_nop 0
	global_load_lds_dwordx4 v[168:169], off
	v_lshl_add_u64 v[168:169], s[42:43], 0, v[184:185]
	s_mov_b32 m0, s46
	s_nop 0
	global_load_lds_dwordx4 v[168:169], off
	v_lshl_add_u64 v[168:169], s[42:43], 0, v[180:181]
	s_mov_b32 m0, s92
	s_nop 0
	global_load_lds_dwordx4 v[168:169], off
	v_lshl_add_u64 v[168:169], v[212:213], 0, s[76:77]
	s_mov_b32 m0, s90
	s_nop 0
	global_load_lds_dwordx4 v[168:169], off
	v_lshl_add_u64 v[168:169], v[172:173], 0, s[76:77]
	s_mov_b32 m0, s91
	s_nop 0
	global_load_lds_dwordx4 v[168:169], off
	s_waitcnt vmcnt(8)
	s_waitcnt lgkmcnt(0)
	s_setprio 1
	s_barrier
	v_mfma_f32_16x16x32_bf16 v[62:65], v[136:139], v[192:195], v[62:65]
	v_mfma_f32_16x16x32_bf16 v[62:65], v[140:143], v[196:199], v[62:65]
	v_mfma_f32_16x16x32_bf16 v[58:61], v[144:147], v[192:195], v[58:61]
	v_mfma_f32_16x16x32_bf16 v[58:61], v[148:151], v[196:199], v[58:61]
	v_mfma_f32_16x16x32_bf16 v[46:49], v[136:139], v[200:203], v[46:49]
	v_mfma_f32_16x16x32_bf16 v[46:49], v[140:143], v[224:227], v[46:49]
	v_mfma_f32_16x16x32_bf16 v[42:45], v[144:147], v[200:203], v[42:45]
	v_mfma_f32_16x16x32_bf16 v[42:45], v[148:151], v[224:227], v[42:45]
	v_mfma_f32_16x16x32_bf16 v[30:33], v[136:139], v[228:231], v[30:33]
	v_mfma_f32_16x16x32_bf16 v[30:33], v[140:143], v[232:235], v[30:33]
	v_mfma_f32_16x16x32_bf16 v[26:29], v[144:147], v[228:231], v[26:29]
	v_mfma_f32_16x16x32_bf16 v[26:29], v[148:151], v[232:235], v[26:29]
	v_mfma_f32_16x16x32_bf16 v[14:17], v[136:139], v[236:239], v[14:17]
	v_mfma_f32_16x16x32_bf16 v[14:17], v[140:143], v[240:243], v[14:17]
	v_mfma_f32_16x16x32_bf16 v[10:13], v[144:147], v[236:239], v[10:13]
	v_mfma_f32_16x16x32_bf16 v[10:13], v[148:151], v[240:243], v[10:13]
	s_setprio 0
	s_setprio 1
	v_mfma_f32_16x16x32_bf16 v[54:57], v[152:155], v[192:195], v[54:57]
	v_mfma_f32_16x16x32_bf16 v[54:57], v[156:159], v[196:199], v[54:57]
	v_mfma_f32_16x16x32_bf16 v[50:53], v[160:163], v[192:195], v[50:53]
	v_mfma_f32_16x16x32_bf16 v[50:53], v[164:167], v[196:199], v[50:53]
	v_mfma_f32_16x16x32_bf16 v[38:41], v[152:155], v[200:203], v[38:41]
	v_mfma_f32_16x16x32_bf16 v[38:41], v[156:159], v[224:227], v[38:41]
	v_mfma_f32_16x16x32_bf16 v[34:37], v[160:163], v[200:203], v[34:37]
	v_mfma_f32_16x16x32_bf16 v[34:37], v[164:167], v[224:227], v[34:37]
	v_mfma_f32_16x16x32_bf16 v[22:25], v[152:155], v[228:231], v[22:25]
	v_mfma_f32_16x16x32_bf16 v[22:25], v[156:159], v[232:235], v[22:25]
	v_mfma_f32_16x16x32_bf16 v[18:21], v[160:163], v[228:231], v[18:21]
	v_mfma_f32_16x16x32_bf16 v[18:21], v[164:167], v[232:235], v[18:21]
	v_mfma_f32_16x16x32_bf16 v[6:9], v[152:155], v[236:239], v[6:9]
	v_mfma_f32_16x16x32_bf16 v[6:9], v[156:159], v[240:243], v[6:9]
	s_setprio 2
	s_barrier
	v_mfma_f32_16x16x32_bf16 v[2:5], v[160:163], v[236:239], v[2:5]
	v_mfma_f32_16x16x32_bf16 v[2:5], v[164:167], v[240:243], v[2:5]
	s_setprio 0
	v_lshl_add_u64 v[132:133], v[132:133], 0, s[86:87]
	v_lshl_add_u64 v[134:135], v[134:135], 0, s[86:87]
	s_mov_b32 s29, s81

; #define PG8_STAGE(bufoff, gbase, voff) do { _Pragma("unroll") for (int _i = 0; _i < 2; ++_i) \
;         __builtin_amdgcn_global_load_lds((const unsigned*)((const char*)(gbase) + (voff)[_i]), (PG8_LAS unsigned*)(lds + (bufoff) + ldsw + _i * 8192), 16, 0, AUX_A); } while (0)
; #define PG8_STAGEB(bufoff, gbase, voff) do { _Pragma("unroll") for (int _i = 0; _i < 2; ++_i) \
;         __builtin_amdgcn_global_load_lds((const unsigned*)((const char*)(gbase) + (voff)[_i]), (PG8_LAS unsigned*)(lds + (bufoff) + ldsw + _i * 8192), 16, 0, AUX_B); } while (0)
; #define PG8_LDA(dst, b, h) do { _Pragma("unroll") for (int m = 0; m < 4; ++m) _Pragma("unroll") for (int k = 0; k < 2; ++k) dst[m][k] = *(const PG8_LAS bf16x8*)(lds + PG8_SA(b, h) + aoff + m * 2048 + k * 1024); } while (0)
; #define PG8_LDB(dst, b, h) do { _Pragma("unroll") for (int n = 0; n < 2; ++n) _Pragma("unroll") for (int k = 0; k < 2; ++k) dst[n][k] = *(const PG8_LAS bf16x8*)(lds + PG8_SB(b, h) + boff + n * 2048 + k * 1024); } while (0)
; #define PG8_WAIT_V(n) asm volatile("s_waitcnt vmcnt(" #n ")" ::: "memory")
; #define PG8_WAIT_L(n) asm volatile("s_waitcnt lgkmcnt(" #n ")" ::: "memory")
; #define PG8_BAR __builtin_amdgcn_s_barrier()
; template <class Epi, class Sched, bool ALIGN_EPI = false, bool SP2 = false>
; __device__ __forceinline__ void gemm_phase(PG8_LAS unsigned char* lds, const Gemm g, const Sched& S, const Epi& E) {
;     ...
;         for (int t = 0; t < nt; t += 2) {
;             const bool last = (t == nt - 2);
;             const char* a1 = PG8_KP(cA, t + 1, rot, nt);
;             const char* a2 = last ? nAr : PG8_KP(cA, t + 2, rot, nt); const char* b2 = last ? nBr : PG8_KP(cB, t + 2, rot, nt);
;             const char* a3 = a2 + kstep; const char* b3 = b2 + kstep;
;             if (last && has_next) S.a_ready(nxt);
;             if constexpr (SP2) {
;             PG8_LDB(B0, 0, 0); PG8_LDB(B1, 0, 1); PG8_SCHED; PG8_LDA(At, 0, 0); PG8_STAGE(PG8_SA(1, 1), a1 + hstep, voffA);
;             PG8_WAIT_V(8); PG8_WAIT_L(0); PG8_BAR; PG8_MMA(0, 0, At, B0); PG8_MMA(0, 1, At, B1); PG8_BAR; PG8_SCHED;
;             PG8_LDA(At, 0, 1); PG8_STAGEB(PG8_SB(0, 0), b2, voffB); PG8_STAGEB(PG8_SB(0, 1), b2 + hstep, voffB); PG8_STAGE(PG8_SA(0, 0), a2, voffA);
;             PG8_WAIT_V(8); PG8_WAIT_L(0); PG8_BAR; PG8_MMA(1, 0, At, B0); PG8_MMA(1, 1, At, B1); PG8_BAR; PG8_SCHED;
.Lrp_936:
.Lpk_936:
	s_add_i32 s81, s29, 2
	s_cmp_lt_u32 s29, 14
	s_cselect_b32 s0, 0, -16
	s_add_i32 s0, s81, s0
	s_ashr_i32 s1, s0, 31
	s_lshl_b64 s[0:1], s[0:1], 7
	s_add_u32 s2, s64, s0
	s_addc_u32 s46, s65, s1
	s_add_u32 s0, s26, s0
	s_addc_u32 s1, s27, s1
	s_cmp_eq_u32 s29, 14
	s_cselect_b32 s57, s15, s46
	s_cselect_b32 s56, s17, s2
	s_cselect_b32 s59, s43, s1
	s_cselect_b32 s58, s78, s0
	s_add_i32 s2, 0, 0x10000
	s_add_i32 s83, s2, s33
	s_add_i32 s46, 0, 0x14000
	s_add_i32 m0, s25, 0xc000
	s_add_i32 s82, s25, 0xe000
	s_add_i32 s84, s83, 0x2000
	s_add_u32 s60, s58, 0x40000
	s_addc_u32 s61, s59, 0
	s_add_i32 s88, s46, s33
	s_add_i32 s89, s88, 0x2000
	s_add_i32 s90, 0, 0x18000
	s_add_i32 s91, 0, 0x1c000
	s_add_u32 s54, s56, 0x40000
	s_addc_u32 s55, s57, 0
	s_add_i32 s1, s90, s33
	s_add_i32 s0, s1, 0x2000
	s_add_u32 s52, s58, 0x40080
	s_addc_u32 s53, s59, 0
	s_add_i32 s47, s91, s33
	s_add_i32 s46, s47, 0x2000
	global_load_lds_dwordx4 v[16:17], off
	s_mov_b32 m0, s82
	s_nop 0
	global_load_lds_dwordx4 v[14:15], off
	s_waitcnt vmcnt(8)
	s_waitcnt lgkmcnt(0)
	s_setprio 1
	s_barrier
	v_mfma_f32_16x16x32_bf16 v[144:147], v[22:25], v[196:199], 0
	v_mfma_f32_16x16x32_bf16 v[144:147], v[34:37], v[200:203], v[144:147]
	v_mfma_f32_16x16x32_bf16 v[140:143], v[38:41], v[196:199], 0
	v_mfma_f32_16x16x32_bf16 v[140:143], v[160:163], v[200:203], v[140:143]
	v_mfma_f32_16x16x32_bf16 v[128:131], v[22:25], v[222:225], 0
	v_mfma_f32_16x16x32_bf16 v[128:131], v[34:37], v[226:229], v[128:131]
	v_mfma_f32_16x16x32_bf16 v[124:127], v[38:41], v[222:225], 0
	v_mfma_f32_16x16x32_bf16 v[124:127], v[160:163], v[226:229], v[124:127]
	v_mfma_f32_16x16x32_bf16 v[112:115], v[22:25], v[230:233], 0
	v_mfma_f32_16x16x32_bf16 v[112:115], v[34:37], v[234:237], v[112:115]
	v_mfma_f32_16x16x32_bf16 v[108:111], v[38:41], v[230:233], 0
	v_mfma_f32_16x16x32_bf16 v[108:111], v[160:163], v[234:237], v[108:111]
	v_mfma_f32_16x16x32_bf16 v[94:97], v[22:25], v[238:241], 0
	v_mfma_f32_16x16x32_bf16 v[94:97], v[34:37], v[242:245], v[94:97]
	v_mfma_f32_16x16x32_bf16 v[90:93], v[38:41], v[238:241], 0
	v_mfma_f32_16x16x32_bf16 v[90:93], v[160:163], v[242:245], v[90:93]
	s_setprio 0
	s_setprio 1
	v_mfma_f32_16x16x32_bf16 v[136:139], v[180:183], v[196:199], 0
	v_mfma_f32_16x16x32_bf16 v[136:139], v[184:187], v[200:203], v[136:139]
	v_mfma_f32_16x16x32_bf16 v[132:135], v[188:191], v[196:199], 0
	v_mfma_f32_16x16x32_bf16 v[132:135], v[192:195], v[200:203], v[132:135]
	v_mfma_f32_16x16x32_bf16 v[120:123], v[180:183], v[222:225], 0
	v_mfma_f32_16x16x32_bf16 v[120:123], v[184:187], v[226:229], v[120:123]
	v_mfma_f32_16x16x32_bf16 v[116:119], v[188:191], v[222:225], 0
	v_mfma_f32_16x16x32_bf16 v[116:119], v[192:195], v[226:229], v[116:119]
	v_mfma_f32_16x16x32_bf16 v[104:107], v[180:183], v[230:233], 0
	v_mfma_f32_16x16x32_bf16 v[104:107], v[184:187], v[234:237], v[104:107]
	v_mfma_f32_16x16x32_bf16 v[100:103], v[188:191], v[230:233], 0
	v_mfma_f32_16x16x32_bf16 v[100:103], v[192:195], v[234:237], v[100:103]
	v_mfma_f32_16x16x32_bf16 v[86:89], v[180:183], v[238:241], 0
	v_mfma_f32_16x16x32_bf16 v[86:89], v[184:187], v[242:245], v[86:89]
	s_setprio 2
	s_barrier
	v_mfma_f32_16x16x32_bf16 v[82:85], v[188:191], v[238:241], 0
	v_mfma_f32_16x16x32_bf16 v[82:85], v[192:195], v[242:245], v[82:85]
	s_setprio 0
	s_mov_b32 m0, s83
	v_lshl_add_u64 v[166:167], s[58:59], 0, v[150:151]
	ds_read_b128 v[196:199], v165 offset:16384
	ds_read_b128 v[200:203], v165 offset:17408
	ds_read_b128 v[222:225], v165 offset:18432
	ds_read_b128 v[226:229], v165 offset:19456
	ds_read_b128 v[230:233], v165 offset:20480
	ds_read_b128 v[234:237], v165 offset:21504
	ds_read_b128 v[238:241], v165 offset:22528
	ds_read_b128 v[242:245], v165 offset:23552
	global_load_lds_dwordx4 v[166:167], off
	v_lshl_add_u64 v[168:169], s[58:59], 0, v[154:155]
	s_mov_b32 m0, s84
	v_lshl_add_u64 v[172:173], s[60:61], 0, v[150:151]
	global_load_lds_dwordx4 v[168:169], off
	s_mov_b32 m0, s88
	v_lshl_add_u64 v[212:213], s[56:57], 0, v[152:153]
	global_load_lds_dwordx4 v[172:173], off
	v_lshl_add_u64 v[172:173], s[60:61], 0, v[154:155]
	s_mov_b32 m0, s89
	s_nop 0
	global_load_lds_dwordx4 v[172:173], off
	v_lshl_add_u64 v[172:173], s[56:57], 0, v[148:149]
	s_mov_b32 m0, s25
	s_nop 0
	global_load_lds_dwordx4 v[172:173], off
	s_mov_b32 m0, s62
	s_nop 0
	global_load_lds_dwordx4 v[212:213], off
	s_waitcnt vmcnt(8)
	s_waitcnt lgkmcnt(0)
	s_setprio 1
	s_barrier
	v_mfma_f32_16x16x32_bf16 v[78:81], v[22:25], v[196:199], 0
	v_mfma_f32_16x16x32_bf16 v[78:81], v[34:37], v[200:203], v[78:81]
	v_mfma_f32_16x16x32_bf16 v[74:77], v[38:41], v[196:199], 0
	v_mfma_f32_16x16x32_bf16 v[74:77], v[160:163], v[200:203], v[74:77]
	v_mfma_f32_16x16x32_bf16 v[62:65], v[22:25], v[222:225], 0
	v_mfma_f32_16x16x32_bf16 v[62:65], v[34:37], v[226:229], v[62:65]
	v_mfma_f32_16x16x32_bf16 v[58:61], v[38:41], v[222:225], 0
	v_mfma_f32_16x16x32_bf16 v[58:61], v[160:163], v[226:229], v[58:61]
	v_mfma_f32_16x16x32_bf16 v[46:49], v[22:25], v[230:233], 0
	v_mfma_f32_16x16x32_bf16 v[46:49], v[34:37], v[234:237], v[46:49]
	v_mfma_f32_16x16x32_bf16 v[42:45], v[38:41], v[230:233], 0
	v_mfma_f32_16x16x32_bf16 v[42:45], v[160:163], v[234:237], v[42:45]
	v_mfma_f32_16x16x32_bf16 v[18:21], v[22:25], v[238:241], 0
	v_mfma_f32_16x16x32_bf16 v[18:21], v[34:37], v[242:245], v[18:21]
	v_mfma_f32_16x16x32_bf16 v[10:13], v[38:41], v[238:241], 0
	v_mfma_f32_16x16x32_bf16 v[10:13], v[160:163], v[242:245], v[10:13]
	s_setprio 0
	s_setprio 1
	v_mfma_f32_16x16x32_bf16 v[50:53], v[188:191], v[222:225], 0
	v_mfma_f32_16x16x32_bf16 v[30:33], v[180:183], v[230:233], 0
	v_mfma_f32_16x16x32_bf16 v[26:29], v[188:191], v[230:233], 0
	v_mfma_f32_16x16x32_bf16 v[6:9], v[180:183], v[238:241], 0
	v_mfma_f32_16x16x32_bf16 v[2:5], v[188:191], v[238:241], 0
	v_mfma_f32_16x16x32_bf16 v[22:25], v[180:183], v[196:199], 0
	v_mfma_f32_16x16x32_bf16 v[34:37], v[188:191], v[196:199], 0
	v_mfma_f32_16x16x32_bf16 v[38:41], v[180:183], v[222:225], 0
	v_mfma_f32_16x16x32_bf16 v[50:53], v[192:195], v[226:229], v[50:53]
	v_mfma_f32_16x16x32_bf16 v[30:33], v[184:187], v[234:237], v[30:33]
	v_mfma_f32_16x16x32_bf16 v[26:29], v[192:195], v[234:237], v[26:29]
	v_mfma_f32_16x16x32_bf16 v[6:9], v[184:187], v[242:245], v[6:9]
	v_mfma_f32_16x16x32_bf16 v[2:5], v[192:195], v[242:245], v[2:5]
	v_mfma_f32_16x16x32_bf16 v[22:25], v[184:187], v[200:203], v[22:25]
	s_setprio 2
	s_barrier
; #define PG8_STAGE(bufoff, gbase, voff) do { _Pragma("unroll") for (int _i = 0; _i < 2; ++_i) \
;         __builtin_amdgcn_global_load_lds((const unsigned*)((const char*)(gbase) + (voff)[_i]), (PG8_LAS unsigned*)(lds + (bufoff) + ldsw + _i * 8192), 16, 0, AUX_A); } while (0)
; #define PG8_STAGEB(bufoff, gbase, voff) do { _Pragma("unroll") for (int _i = 0; _i < 2; ++_i) \
;         __builtin_amdgcn_global_load_lds((const unsigned*)((const char*)(gbase) + (voff)[_i]), (PG8_LAS unsigned*)(lds + (bufoff) + ldsw + _i * 8192), 16, 0, AUX_B); } while (0)
; #define PG8_LDA(dst, b, h) do { _Pragma("unroll") for (int m = 0; m < 4; ++m) _Pragma("unroll") for (int k = 0; k < 2; ++k) dst[m][k] = *(const PG8_LAS bf16x8*)(lds + PG8_SA(b, h) + aoff + m * 2048 + k * 1024); } while (0)
; #define PG8_LDB(dst, b, h) do { _Pragma("unroll") for (int n = 0; n < 2; ++n) _Pragma("unroll") for (int k = 0; k < 2; ++k) dst[n][k] = *(const PG8_LAS bf16x8*)(lds + PG8_SB(b, h) + boff + n * 2048 + k * 1024); } while (0)
; #define PG8_MMA(ai, bj, At, Bt) do { __builtin_amdgcn_s_setprio(1); _Pragma("unroll") for (int m = 0; m < 4; ++m) _Pragma("unroll") for (int n = 0; n < 2; ++n) _Pragma("unroll") for (int k = 0; k < 2; ++k) \
;         acc[ai][bj][m][n] = __builtin_amdgcn_mfma_f32_16x16x32_bf16(Bt[n][k], At[m][k], acc[ai][bj][m][n], 0, 0, 0); __builtin_amdgcn_s_setprio(0); } while (0)
; #define PG8_WAIT_V(n) asm volatile("s_waitcnt vmcnt(" #n ")" ::: "memory")
; #define PG8_WAIT_L(n) asm volatile("s_waitcnt lgkmcnt(" #n ")" ::: "memory")
; #define PG8_BAR __builtin_amdgcn_s_barrier()
; #define PG8_SCHED __builtin_amdgcn_sched_barrier(0)
; template <class Epi, class Sched, bool ALIGN_EPI = false, bool SP2 = false>
; __device__ __forceinline__ void gemm_phase(PG8_LAS unsigned char* lds, const Gemm g, const Sched& S, const Epi& E) {
;     ...
;         for (int t = 0; t < nt; t += 2) {
;     ...
;             PG8_LDB(B0, 1, 0); PG8_LDB(B1, 1, 1); PG8_SCHED; PG8_LDA(At, 1, 0); PG8_STAGE(PG8_SA(0, 1), a2 + hstep, voffA);
;             PG8_WAIT_V(8); PG8_WAIT_L(0); PG8_BAR; PG8_MMA(0, 0, At, B0); PG8_MMA(0, 1, At, B1); PG8_BAR; PG8_SCHED;
;             PG8_LDA(At, 1, 1); PG8_STAGEB(PG8_SB(1, 0), b3, voffB); PG8_STAGEB(PG8_SB(1, 1), b3 + hstep, voffB); PG8_STAGE(PG8_SA(1, 0), a3, voffA);
;             PG8_WAIT_V(8); PG8_WAIT_L(0); PG8_BAR; PG8_MMA(1, 0, At, B0); PG8_MMA(1, 1, At, B1); PG8_BAR; PG8_SCHED;
	v_mfma_f32_16x16x32_bf16 v[34:37], v[192:195], v[200:203], v[34:37]
	v_mfma_f32_16x16x32_bf16 v[38:41], v[184:187], v[226:229], v[38:41]
	s_setprio 0
	v_add_u32_e32 v160, s90, v99
	v_add_u32_e32 v192, s91, v99
	ds_read_b128 v[54:57], v160
	ds_read_b128 v[66:69], v160 offset:1024
	ds_read_b128 v[70:73], v160 offset:2048
	ds_read_b128 v[160:163], v160 offset:3072
	ds_read_b128 v[180:183], v192
	ds_read_b128 v[184:187], v192 offset:1024
	ds_read_b128 v[188:191], v192 offset:2048
	ds_read_b128 v[192:195], v192 offset:3072
	s_mov_b32 m0, s63
	v_lshl_add_u64 v[246:247], s[54:55], 0, v[148:149]
	ds_read_b128 v[196:199], v165 offset:32768
	ds_read_b128 v[200:203], v165 offset:33792
	ds_read_b128 v[222:225], v165 offset:34816
	ds_read_b128 v[226:229], v165 offset:35840
	ds_read_b128 v[230:233], v165 offset:36864
	ds_read_b128 v[234:237], v165 offset:37888
	ds_read_b128 v[238:241], v165 offset:38912
	ds_read_b128 v[242:245], v165 offset:39936
	global_load_lds_dwordx4 v[246:247], off
	v_lshl_add_u64 v[246:247], s[54:55], 0, v[152:153]
	s_mov_b32 m0, s69
	s_nop 0
	global_load_lds_dwordx4 v[246:247], off
	s_waitcnt vmcnt(8)
	s_waitcnt lgkmcnt(0)
	s_setprio 1
	s_barrier
	v_mfma_f32_16x16x32_bf16 v[144:147], v[54:57], v[196:199], v[144:147]
	v_mfma_f32_16x16x32_bf16 v[144:147], v[66:69], v[200:203], v[144:147]
	v_mfma_f32_16x16x32_bf16 v[140:143], v[70:73], v[196:199], v[140:143]
	v_mfma_f32_16x16x32_bf16 v[140:143], v[160:163], v[200:203], v[140:143]
	v_mfma_f32_16x16x32_bf16 v[128:131], v[54:57], v[222:225], v[128:131]
	v_mfma_f32_16x16x32_bf16 v[128:131], v[66:69], v[226:229], v[128:131]
	v_mfma_f32_16x16x32_bf16 v[124:127], v[70:73], v[222:225], v[124:127]
	v_mfma_f32_16x16x32_bf16 v[124:127], v[160:163], v[226:229], v[124:127]
	v_mfma_f32_16x16x32_bf16 v[112:115], v[54:57], v[230:233], v[112:115]
	v_mfma_f32_16x16x32_bf16 v[112:115], v[66:69], v[234:237], v[112:115]
	v_mfma_f32_16x16x32_bf16 v[108:111], v[70:73], v[230:233], v[108:111]
	v_mfma_f32_16x16x32_bf16 v[108:111], v[160:163], v[234:237], v[108:111]
	v_mfma_f32_16x16x32_bf16 v[94:97], v[54:57], v[238:241], v[94:97]
	v_mfma_f32_16x16x32_bf16 v[94:97], v[66:69], v[242:245], v[94:97]
	v_mfma_f32_16x16x32_bf16 v[90:93], v[70:73], v[238:241], v[90:93]
	v_mfma_f32_16x16x32_bf16 v[90:93], v[160:163], v[242:245], v[90:93]
	s_setprio 0
	s_setprio 1
	v_mfma_f32_16x16x32_bf16 v[136:139], v[180:183], v[196:199], v[136:139]
	v_mfma_f32_16x16x32_bf16 v[136:139], v[184:187], v[200:203], v[136:139]
	v_mfma_f32_16x16x32_bf16 v[132:135], v[188:191], v[196:199], v[132:135]
	v_mfma_f32_16x16x32_bf16 v[132:135], v[192:195], v[200:203], v[132:135]
	v_mfma_f32_16x16x32_bf16 v[120:123], v[180:183], v[222:225], v[120:123]
	v_mfma_f32_16x16x32_bf16 v[120:123], v[184:187], v[226:229], v[120:123]
	v_mfma_f32_16x16x32_bf16 v[116:119], v[188:191], v[222:225], v[116:119]
	v_mfma_f32_16x16x32_bf16 v[116:119], v[192:195], v[226:229], v[116:119]
	v_mfma_f32_16x16x32_bf16 v[104:107], v[180:183], v[230:233], v[104:107]
	v_mfma_f32_16x16x32_bf16 v[104:107], v[184:187], v[234:237], v[104:107]
	v_mfma_f32_16x16x32_bf16 v[100:103], v[188:191], v[230:233], v[100:103]
	v_mfma_f32_16x16x32_bf16 v[100:103], v[192:195], v[234:237], v[100:103]
	v_mfma_f32_16x16x32_bf16 v[86:89], v[180:183], v[238:241], v[86:89]
	v_mfma_f32_16x16x32_bf16 v[86:89], v[184:187], v[242:245], v[86:89]
	s_setprio 2
	s_barrier
	v_mfma_f32_16x16x32_bf16 v[82:85], v[188:191], v[238:241], v[82:85]
	v_mfma_f32_16x16x32_bf16 v[82:85], v[192:195], v[242:245], v[82:85]
	s_setprio 0
	s_mov_b32 m0, s1
	v_lshl_add_u64 v[166:167], v[166:167], 0, s[76:77]
	ds_read_b128 v[196:199], v165 offset:49152
	ds_read_b128 v[200:203], v165 offset:50176
	ds_read_b128 v[222:225], v165 offset:51200
	ds_read_b128 v[226:229], v165 offset:52224
	ds_read_b128 v[230:233], v165 offset:53248
	ds_read_b128 v[234:237], v165 offset:54272
	ds_read_b128 v[238:241], v165 offset:55296
	ds_read_b128 v[242:245], v165 offset:56320
	global_load_lds_dwordx4 v[166:167], off
	v_lshl_add_u64 v[166:167], v[168:169], 0, s[76:77]
	s_mov_b32 m0, s0
	s_nop 0
	global_load_lds_dwordx4 v[166:167], off
	v_lshl_add_u64 v[166:167], s[52:53], 0, v[150:151]
	s_mov_b32 m0, s47
	s_nop 0
	global_load_lds_dwordx4 v[166:167], off
	v_lshl_add_u64 v[166:167], s[52:53], 0, v[154:155]
	s_mov_b32 m0, s46
	s_nop 0
	global_load_lds_dwordx4 v[166:167], off
	v_lshl_add_u64 v[166:167], v[172:173], 0, s[76:77]
	s_mov_b32 m0, s70
	s_nop 0
	global_load_lds_dwordx4 v[166:167], off
	v_lshl_add_u64 v[166:167], v[212:213], 0, s[76:77]
	s_mov_b32 m0, s71
	s_nop 0
	global_load_lds_dwordx4 v[166:167], off
	s_waitcnt vmcnt(8)
	s_waitcnt lgkmcnt(0)
	s_setprio 1
	s_barrier
	v_mfma_f32_16x16x32_bf16 v[78:81], v[54:57], v[196:199], v[78:81]
	v_mfma_f32_16x16x32_bf16 v[78:81], v[66:69], v[200:203], v[78:81]
	v_mfma_f32_16x16x32_bf16 v[74:77], v[70:73], v[196:199], v[74:77]
	v_mfma_f32_16x16x32_bf16 v[74:77], v[160:163], v[200:203], v[74:77]
	v_mfma_f32_16x16x32_bf16 v[62:65], v[54:57], v[222:225], v[62:65]
	v_mfma_f32_16x16x32_bf16 v[62:65], v[66:69], v[226:229], v[62:65]
	v_mfma_f32_16x16x32_bf16 v[58:61], v[70:73], v[222:225], v[58:61]
	v_mfma_f32_16x16x32_bf16 v[58:61], v[160:163], v[226:229], v[58:61]
	v_mfma_f32_16x16x32_bf16 v[46:49], v[54:57], v[230:233], v[46:49]
	v_mfma_f32_16x16x32_bf16 v[46:49], v[66:69], v[234:237], v[46:49]
	v_mfma_f32_16x16x32_bf16 v[42:45], v[70:73], v[230:233], v[42:45]
	v_mfma_f32_16x16x32_bf16 v[42:45], v[160:163], v[234:237], v[42:45]
	v_mfma_f32_16x16x32_bf16 v[18:21], v[54:57], v[238:241], v[18:21]
	v_mfma_f32_16x16x32_bf16 v[18:21], v[66:69], v[242:245], v[18:21]
	v_mfma_f32_16x16x32_bf16 v[10:13], v[70:73], v[238:241], v[10:13]
	v_mfma_f32_16x16x32_bf16 v[10:13], v[160:163], v[242:245], v[10:13]
	s_setprio 0
	s_setprio 1
	v_mfma_f32_16x16x32_bf16 v[22:25], v[180:183], v[196:199], v[22:25]
	v_mfma_f32_16x16x32_bf16 v[70:73], v[184:187], v[200:203], v[22:25]
	v_mfma_f32_16x16x32_bf16 v[22:25], v[188:191], v[196:199], v[34:37]
	v_mfma_f32_16x16x32_bf16 v[66:69], v[192:195], v[200:203], v[22:25]
	v_mfma_f32_16x16x32_bf16 v[22:25], v[180:183], v[222:225], v[38:41]
	v_mfma_f32_16x16x32_bf16 v[54:57], v[184:187], v[226:229], v[22:25]
	v_mfma_f32_16x16x32_bf16 v[22:25], v[188:191], v[222:225], v[50:53]
	v_mfma_f32_16x16x32_bf16 v[50:53], v[192:195], v[226:229], v[22:25]
	v_mfma_f32_16x16x32_bf16 v[22:25], v[180:183], v[230:233], v[30:33]
	v_mfma_f32_16x16x32_bf16 v[30:33], v[184:187], v[234:237], v[22:25]
	v_mfma_f32_16x16x32_bf16 v[22:25], v[188:191], v[230:233], v[26:29]
	v_mfma_f32_16x16x32_bf16 v[6:9], v[180:183], v[238:241], v[6:9]
	v_mfma_f32_16x16x32_bf16 v[2:5], v[188:191], v[238:241], v[2:5]
	v_mfma_f32_16x16x32_bf16 v[26:29], v[192:195], v[234:237], v[22:25]
	s_setprio 2
	s_barrier
	v_mfma_f32_16x16x32_bf16 v[6:9], v[184:187], v[242:245], v[6:9]
	v_mfma_f32_16x16x32_bf16 v[2:5], v[192:195], v[242:245], v[2:5]
	s_setprio 0
	v_lshl_add_u64 v[14:15], v[14:15], 0, s[86:87]
	v_lshl_add_u64 v[16:17], v[16:17], 0, s[86:87]
	s_mov_b32 s29, s81

; #define PG8_STAGE(bufoff, gbase, voff) do { _Pragma("unroll") for (int _i = 0; _i < 2; ++_i) \
;         __builtin_amdgcn_global_load_lds((const unsigned*)((const char*)(gbase) + (voff)[_i]), (PG8_LAS unsigned*)(lds + (bufoff) + ldsw + _i * 8192), 16, 0, AUX_A); } while (0)
; #define PG8_STAGEB(bufoff, gbase, voff) do { _Pragma("unroll") for (int _i = 0; _i < 2; ++_i) \
;         __builtin_amdgcn_global_load_lds((const unsigned*)((const char*)(gbase) + (voff)[_i]), (PG8_LAS unsigned*)(lds + (bufoff) + ldsw + _i * 8192), 16, 0, AUX_B); } while (0)
; #define PG8_LDA(dst, b, h) do { _Pragma("unroll") for (int m = 0; m < 4; ++m) _Pragma("unroll") for (int k = 0; k < 2; ++k) dst[m][k] = *(const PG8_LAS bf16x8*)(lds + PG8_SA(b, h) + aoff + m * 2048 + k * 1024); } while (0)
; #define PG8_LDB(dst, b, h) do { _Pragma("unroll") for (int n = 0; n < 2; ++n) _Pragma("unroll") for (int k = 0; k < 2; ++k) dst[n][k] = *(const PG8_LAS bf16x8*)(lds + PG8_SB(b, h) + boff + n * 2048 + k * 1024); } while (0)
; #define PG8_WAIT_V(n) asm volatile("s_waitcnt vmcnt(" #n ")" ::: "memory")
; #define PG8_WAIT_L(n) asm volatile("s_waitcnt lgkmcnt(" #n ")" ::: "memory")
; #define PG8_BAR __builtin_amdgcn_s_barrier()
; template <class Epi, class Sched, bool ALIGN_EPI = false, bool SP2 = false>
; __device__ __forceinline__ void gemm_phase(PG8_LAS unsigned char* lds, const Gemm g, const Sched& S, const Epi& E) {
;     ...
;         for (int t = 0; t < nt; t += 2) {
;             const bool last = (t == nt - 2);
;             const char* a1 = PG8_KP(cA, t + 1, rot, nt);
;             const char* a2 = last ? nAr : PG8_KP(cA, t + 2, rot, nt); const char* b2 = last ? nBr : PG8_KP(cB, t + 2, rot, nt);
;             const char* a3 = a2 + kstep; const char* b3 = b2 + kstep;
;             if (last && has_next) S.a_ready(nxt);
;             if constexpr (SP2) {
;             PG8_LDB(B0, 0, 0); PG8_LDB(B1, 0, 1); PG8_SCHED; PG8_LDA(At, 0, 0); PG8_STAGE(PG8_SA(1, 1), a1 + hstep, voffA);
;             PG8_WAIT_V(8); PG8_WAIT_L(0); PG8_BAR; PG8_MMA(0, 0, At, B0); PG8_MMA(0, 1, At, B1); PG8_BAR; PG8_SCHED;
;             PG8_LDA(At, 0, 1); PG8_STAGEB(PG8_SB(0, 0), b2, voffB); PG8_STAGEB(PG8_SB(0, 1), b2 + hstep, voffB); PG8_STAGE(PG8_SA(0, 0), a2, voffA);
;             PG8_WAIT_V(8); PG8_WAIT_L(0); PG8_BAR; PG8_MMA(1, 0, At, B0); PG8_MMA(1, 1, At, B1); PG8_BAR; PG8_SCHED;
.Lrp_1067:
.Lpk_1067:
	s_add_i32 s81, s29, 2
	s_cmp_lt_u32 s29, 14
	s_cselect_b32 s0, 0, -16
	s_add_i32 s0, s81, s0
	s_ashr_i32 s1, s0, 31
	s_lshl_b64 s[0:1], s[0:1], 7
	s_add_u32 s2, s52, s0
	s_addc_u32 s46, s53, s1
	s_add_u32 s0, s42, s0
	s_addc_u32 s1, s43, s1
	s_cmp_eq_u32 s29, 14
	s_cselect_b32 s59, s15, s46
	s_cselect_b32 s58, s17, s2
	s_cselect_b32 s61, s92, s1
	s_cselect_b32 s60, s93, s0
	s_add_i32 s2, 0, 0x10000
	s_add_i32 s94, s2, s70
	s_add_i32 s46, 0, 0x14000
	s_add_i32 m0, s71, 0xc000
	s_add_i32 s84, s71, 0xe000
	s_add_i32 s95, s94, 0x2000
	s_add_u32 s62, s60, 0x40000
	s_addc_u32 s63, s61, 0
	s_add_i32 s96, s46, s70
	s_add_i32 s97, s96, 0x2000
	s_add_i32 vcc_lo, 0, 0x18000
	s_add_i32 vcc_hi, 0, 0x1c000
	s_add_u32 s56, s58, 0x40000
	s_addc_u32 s57, s59, 0
	s_add_i32 s1, vcc_lo, s70
	s_add_i32 s0, s1, 0x2000
	s_add_u32 s54, s60, 0x40080
	s_addc_u32 s55, s61, 0
	s_add_i32 s47, vcc_hi, s70
	s_add_i32 s46, s47, 0x2000
	global_load_lds_dwordx4 v[146:147], off
	s_mov_b32 m0, s84
	s_nop 0
	global_load_lds_dwordx4 v[144:145], off
	s_waitcnt vmcnt(8)
	s_waitcnt lgkmcnt(0)
	s_setprio 1
	s_barrier
	v_mfma_f32_16x16x32_bf16 v[128:131], v[152:155], v[196:199], 0
	v_mfma_f32_16x16x32_bf16 v[128:131], v[156:159], v[200:203], v[128:131]
	v_mfma_f32_16x16x32_bf16 v[124:127], v[160:163], v[196:199], 0
	v_mfma_f32_16x16x32_bf16 v[124:127], v[164:167], v[200:203], v[124:127]
	v_mfma_f32_16x16x32_bf16 v[112:115], v[152:155], v[222:225], 0
	v_mfma_f32_16x16x32_bf16 v[112:115], v[156:159], v[226:229], v[112:115]
	v_mfma_f32_16x16x32_bf16 v[108:111], v[160:163], v[222:225], 0
	v_mfma_f32_16x16x32_bf16 v[108:111], v[164:167], v[226:229], v[108:111]
	v_mfma_f32_16x16x32_bf16 v[94:97], v[152:155], v[230:233], 0
	v_mfma_f32_16x16x32_bf16 v[94:97], v[156:159], v[234:237], v[94:97]
	v_mfma_f32_16x16x32_bf16 v[90:93], v[160:163], v[230:233], 0
	v_mfma_f32_16x16x32_bf16 v[90:93], v[164:167], v[234:237], v[90:93]
	v_mfma_f32_16x16x32_bf16 v[78:81], v[152:155], v[238:241], 0
	v_mfma_f32_16x16x32_bf16 v[78:81], v[156:159], v[242:245], v[78:81]
	v_mfma_f32_16x16x32_bf16 v[74:77], v[160:163], v[238:241], 0
	v_mfma_f32_16x16x32_bf16 v[74:77], v[164:167], v[242:245], v[74:77]
	s_setprio 0
	s_setprio 1
	v_mfma_f32_16x16x32_bf16 v[120:123], v[180:183], v[196:199], 0
	v_mfma_f32_16x16x32_bf16 v[120:123], v[184:187], v[200:203], v[120:123]
	v_mfma_f32_16x16x32_bf16 v[116:119], v[188:191], v[196:199], 0
	v_mfma_f32_16x16x32_bf16 v[116:119], v[192:195], v[200:203], v[116:119]
	v_mfma_f32_16x16x32_bf16 v[104:107], v[180:183], v[222:225], 0
	v_mfma_f32_16x16x32_bf16 v[104:107], v[184:187], v[226:229], v[104:107]
	v_mfma_f32_16x16x32_bf16 v[100:103], v[188:191], v[222:225], 0
	v_mfma_f32_16x16x32_bf16 v[100:103], v[192:195], v[226:229], v[100:103]
	v_mfma_f32_16x16x32_bf16 v[86:89], v[180:183], v[230:233], 0
	v_mfma_f32_16x16x32_bf16 v[86:89], v[184:187], v[234:237], v[86:89]
	v_mfma_f32_16x16x32_bf16 v[82:85], v[188:191], v[230:233], 0
	v_mfma_f32_16x16x32_bf16 v[82:85], v[192:195], v[234:237], v[82:85]
	v_mfma_f32_16x16x32_bf16 v[70:73], v[180:183], v[238:241], 0
	v_mfma_f32_16x16x32_bf16 v[70:73], v[184:187], v[242:245], v[70:73]
	s_setprio 2
	s_barrier
	v_mfma_f32_16x16x32_bf16 v[66:69], v[188:191], v[238:241], 0
	v_mfma_f32_16x16x32_bf16 v[66:69], v[192:195], v[242:245], v[66:69]
	s_setprio 0
	s_mov_b32 m0, s94
	v_lshl_add_u64 v[148:149], s[60:61], 0, v[136:137]
	ds_read_b128 v[196:199], v151 offset:16384
	ds_read_b128 v[200:203], v151 offset:17408
	ds_read_b128 v[222:225], v151 offset:18432
	ds_read_b128 v[226:229], v151 offset:19456
	ds_read_b128 v[230:233], v151 offset:20480
	ds_read_b128 v[234:237], v151 offset:21504
	ds_read_b128 v[238:241], v151 offset:22528
	ds_read_b128 v[242:245], v151 offset:23552
	global_load_lds_dwordx4 v[148:149], off
	v_lshl_add_u64 v[168:169], s[60:61], 0, v[132:133]
	s_mov_b32 m0, s95
	v_lshl_add_u64 v[172:173], s[62:63], 0, v[136:137]
	global_load_lds_dwordx4 v[168:169], off
	s_mov_b32 m0, s96
	v_lshl_add_u64 v[212:213], s[58:59], 0, v[134:135]
	global_load_lds_dwordx4 v[172:173], off
	v_lshl_add_u64 v[172:173], s[62:63], 0, v[132:133]
	s_mov_b32 m0, s97
	s_nop 0
	global_load_lds_dwordx4 v[172:173], off
	v_lshl_add_u64 v[172:173], s[58:59], 0, v[138:139]
	s_mov_b32 m0, s71
	s_nop 0
	global_load_lds_dwordx4 v[172:173], off
	s_mov_b32 m0, s75
	s_nop 0
	global_load_lds_dwordx4 v[212:213], off
	s_waitcnt vmcnt(8)
	s_waitcnt lgkmcnt(0)
	s_setprio 1
	s_barrier
	v_mfma_f32_16x16x32_bf16 v[62:65], v[152:155], v[196:199], 0
	v_mfma_f32_16x16x32_bf16 v[62:65], v[156:159], v[200:203], v[62:65]
	v_mfma_f32_16x16x32_bf16 v[58:61], v[160:163], v[196:199], 0
	v_mfma_f32_16x16x32_bf16 v[58:61], v[164:167], v[200:203], v[58:61]
	v_mfma_f32_16x16x32_bf16 v[46:49], v[152:155], v[222:225], 0
	v_mfma_f32_16x16x32_bf16 v[46:49], v[156:159], v[226:229], v[46:49]
	v_mfma_f32_16x16x32_bf16 v[42:45], v[160:163], v[222:225], 0
	v_mfma_f32_16x16x32_bf16 v[42:45], v[164:167], v[226:229], v[42:45]
	v_mfma_f32_16x16x32_bf16 v[30:33], v[152:155], v[230:233], 0
	v_mfma_f32_16x16x32_bf16 v[30:33], v[156:159], v[234:237], v[30:33]
	v_mfma_f32_16x16x32_bf16 v[26:29], v[160:163], v[230:233], 0
	v_mfma_f32_16x16x32_bf16 v[26:29], v[164:167], v[234:237], v[26:29]
	v_mfma_f32_16x16x32_bf16 v[14:17], v[152:155], v[238:241], 0
	v_mfma_f32_16x16x32_bf16 v[14:17], v[156:159], v[242:245], v[14:17]
	v_mfma_f32_16x16x32_bf16 v[10:13], v[160:163], v[238:241], 0
	v_mfma_f32_16x16x32_bf16 v[10:13], v[164:167], v[242:245], v[10:13]
	s_setprio 0
	s_setprio 1
	v_mfma_f32_16x16x32_bf16 v[54:57], v[180:183], v[196:199], 0
	v_mfma_f32_16x16x32_bf16 v[54:57], v[184:187], v[200:203], v[54:57]
	v_mfma_f32_16x16x32_bf16 v[50:53], v[188:191], v[196:199], 0
	v_mfma_f32_16x16x32_bf16 v[50:53], v[192:195], v[200:203], v[50:53]
	v_mfma_f32_16x16x32_bf16 v[38:41], v[180:183], v[222:225], 0
	v_mfma_f32_16x16x32_bf16 v[38:41], v[184:187], v[226:229], v[38:41]
	v_mfma_f32_16x16x32_bf16 v[34:37], v[188:191], v[222:225], 0
	v_mfma_f32_16x16x32_bf16 v[34:37], v[192:195], v[226:229], v[34:37]
	v_mfma_f32_16x16x32_bf16 v[22:25], v[180:183], v[230:233], 0
	v_mfma_f32_16x16x32_bf16 v[22:25], v[184:187], v[234:237], v[22:25]
	v_mfma_f32_16x16x32_bf16 v[18:21], v[188:191], v[230:233], 0
	v_mfma_f32_16x16x32_bf16 v[18:21], v[192:195], v[234:237], v[18:21]
	v_mfma_f32_16x16x32_bf16 v[6:9], v[180:183], v[238:241], 0
	v_mfma_f32_16x16x32_bf16 v[6:9], v[184:187], v[242:245], v[6:9]
	s_setprio 2
	s_barrier
; #define PG8_STAGE(bufoff, gbase, voff) do { _Pragma("unroll") for (int _i = 0; _i < 2; ++_i) \
;         __builtin_amdgcn_global_load_lds((const unsigned*)((const char*)(gbase) + (voff)[_i]), (PG8_LAS unsigned*)(lds + (bufoff) + ldsw + _i * 8192), 16, 0, AUX_A); } while (0)
; #define PG8_STAGEB(bufoff, gbase, voff) do { _Pragma("unroll") for (int _i = 0; _i < 2; ++_i) \
;         __builtin_amdgcn_global_load_lds((const unsigned*)((const char*)(gbase) + (voff)[_i]), (PG8_LAS unsigned*)(lds + (bufoff) + ldsw + _i * 8192), 16, 0, AUX_B); } while (0)
; #define PG8_LDA(dst, b, h) do { _Pragma("unroll") for (int m = 0; m < 4; ++m) _Pragma("unroll") for (int k = 0; k < 2; ++k) dst[m][k] = *(const PG8_LAS bf16x8*)(lds + PG8_SA(b, h) + aoff + m * 2048 + k * 1024); } while (0)
; #define PG8_LDB(dst, b, h) do { _Pragma("unroll") for (int n = 0; n < 2; ++n) _Pragma("unroll") for (int k = 0; k < 2; ++k) dst[n][k] = *(const PG8_LAS bf16x8*)(lds + PG8_SB(b, h) + boff + n * 2048 + k * 1024); } while (0)
; #define PG8_MMA(ai, bj, At, Bt) do { __builtin_amdgcn_s_setprio(1); _Pragma("unroll") for (int m = 0; m < 4; ++m) _Pragma("unroll") for (int n = 0; n < 2; ++n) _Pragma("unroll") for (int k = 0; k < 2; ++k) \
;         acc[ai][bj][m][n] = __builtin_amdgcn_mfma_f32_16x16x32_bf16(Bt[n][k], At[m][k], acc[ai][bj][m][n], 0, 0, 0); __builtin_amdgcn_s_setprio(0); } while (0)
; #define PG8_WAIT_V(n) asm volatile("s_waitcnt vmcnt(" #n ")" ::: "memory")
; #define PG8_WAIT_L(n) asm volatile("s_waitcnt lgkmcnt(" #n ")" ::: "memory")
; #define PG8_BAR __builtin_amdgcn_s_barrier()
; #define PG8_SCHED __builtin_amdgcn_sched_barrier(0)
; template <class Epi, class Sched, bool ALIGN_EPI = false, bool SP2 = false>
; __device__ __forceinline__ void gemm_phase(PG8_LAS unsigned char* lds, const Gemm g, const Sched& S, const Epi& E) {
;     ...
;         for (int t = 0; t < nt; t += 2) {
;     ...
;             PG8_LDB(B0, 1, 0); PG8_LDB(B1, 1, 1); PG8_SCHED; PG8_LDA(At, 1, 0); PG8_STAGE(PG8_SA(0, 1), a2 + hstep, voffA);
;             PG8_WAIT_V(8); PG8_WAIT_L(0); PG8_BAR; PG8_MMA(0, 0, At, B0); PG8_MMA(0, 1, At, B1); PG8_BAR; PG8_SCHED;
;             PG8_LDA(At, 1, 1); PG8_STAGEB(PG8_SB(1, 0), b3, voffB); PG8_STAGEB(PG8_SB(1, 1), b3 + hstep, voffB); PG8_STAGE(PG8_SA(1, 0), a3, voffA);
;             PG8_WAIT_V(8); PG8_WAIT_L(0); PG8_BAR; PG8_MMA(1, 0, At, B0); PG8_MMA(1, 1, At, B1); PG8_BAR; PG8_SCHED;
	v_mfma_f32_16x16x32_bf16 v[2:5], v[188:191], v[238:241], 0
	v_mfma_f32_16x16x32_bf16 v[2:5], v[192:195], v[242:245], v[2:5]
	s_setprio 0
	v_add_u32_e32 v164, vcc_lo, v99
	v_add_u32_e32 v192, vcc_hi, v99
	ds_read_b128 v[152:155], v164
	ds_read_b128 v[156:159], v164 offset:1024
	ds_read_b128 v[160:163], v164 offset:2048
	ds_read_b128 v[164:167], v164 offset:3072
	ds_read_b128 v[180:183], v192
	ds_read_b128 v[184:187], v192 offset:1024
	ds_read_b128 v[188:191], v192 offset:2048
	ds_read_b128 v[192:195], v192 offset:3072
	s_mov_b32 m0, s78
	v_lshl_add_u64 v[246:247], s[56:57], 0, v[138:139]
	ds_read_b128 v[196:199], v151 offset:32768
	ds_read_b128 v[200:203], v151 offset:33792
	ds_read_b128 v[222:225], v151 offset:34816
	ds_read_b128 v[226:229], v151 offset:35840
	ds_read_b128 v[230:233], v151 offset:36864
	ds_read_b128 v[234:237], v151 offset:37888
	ds_read_b128 v[238:241], v151 offset:38912
	ds_read_b128 v[242:245], v151 offset:39936
	global_load_lds_dwordx4 v[246:247], off
	v_lshl_add_u64 v[246:247], s[56:57], 0, v[134:135]
	s_mov_b32 m0, s82
	s_nop 0
	global_load_lds_dwordx4 v[246:247], off
	s_waitcnt vmcnt(8)
	s_waitcnt lgkmcnt(0)
	s_setprio 1
	s_barrier
	v_mfma_f32_16x16x32_bf16 v[128:131], v[152:155], v[196:199], v[128:131]
	v_mfma_f32_16x16x32_bf16 v[128:131], v[156:159], v[200:203], v[128:131]
	v_mfma_f32_16x16x32_bf16 v[124:127], v[160:163], v[196:199], v[124:127]
	v_mfma_f32_16x16x32_bf16 v[124:127], v[164:167], v[200:203], v[124:127]
	v_mfma_f32_16x16x32_bf16 v[112:115], v[152:155], v[222:225], v[112:115]
	v_mfma_f32_16x16x32_bf16 v[112:115], v[156:159], v[226:229], v[112:115]
	v_mfma_f32_16x16x32_bf16 v[108:111], v[160:163], v[222:225], v[108:111]
	v_mfma_f32_16x16x32_bf16 v[108:111], v[164:167], v[226:229], v[108:111]
	v_mfma_f32_16x16x32_bf16 v[94:97], v[152:155], v[230:233], v[94:97]
	v_mfma_f32_16x16x32_bf16 v[94:97], v[156:159], v[234:237], v[94:97]
	v_mfma_f32_16x16x32_bf16 v[90:93], v[160:163], v[230:233], v[90:93]
	v_mfma_f32_16x16x32_bf16 v[90:93], v[164:167], v[234:237], v[90:93]
	v_mfma_f32_16x16x32_bf16 v[78:81], v[152:155], v[238:241], v[78:81]
	v_mfma_f32_16x16x32_bf16 v[78:81], v[156:159], v[242:245], v[78:81]
	v_mfma_f32_16x16x32_bf16 v[74:77], v[160:163], v[238:241], v[74:77]
	v_mfma_f32_16x16x32_bf16 v[74:77], v[164:167], v[242:245], v[74:77]
	s_setprio 0
	s_setprio 1
	v_mfma_f32_16x16x32_bf16 v[120:123], v[180:183], v[196:199], v[120:123]
	v_mfma_f32_16x16x32_bf16 v[120:123], v[184:187], v[200:203], v[120:123]
	v_mfma_f32_16x16x32_bf16 v[116:119], v[188:191], v[196:199], v[116:119]
	v_mfma_f32_16x16x32_bf16 v[116:119], v[192:195], v[200:203], v[116:119]
	v_mfma_f32_16x16x32_bf16 v[104:107], v[180:183], v[222:225], v[104:107]
	v_mfma_f32_16x16x32_bf16 v[104:107], v[184:187], v[226:229], v[104:107]
	v_mfma_f32_16x16x32_bf16 v[100:103], v[188:191], v[222:225], v[100:103]
	v_mfma_f32_16x16x32_bf16 v[100:103], v[192:195], v[226:229], v[100:103]
	v_mfma_f32_16x16x32_bf16 v[86:89], v[180:183], v[230:233], v[86:89]
	v_mfma_f32_16x16x32_bf16 v[86:89], v[184:187], v[234:237], v[86:89]
	v_mfma_f32_16x16x32_bf16 v[82:85], v[188:191], v[230:233], v[82:85]
	v_mfma_f32_16x16x32_bf16 v[82:85], v[192:195], v[234:237], v[82:85]
	v_mfma_f32_16x16x32_bf16 v[70:73], v[180:183], v[238:241], v[70:73]
	v_mfma_f32_16x16x32_bf16 v[70:73], v[184:187], v[242:245], v[70:73]
	s_setprio 2
	s_barrier
	v_mfma_f32_16x16x32_bf16 v[66:69], v[188:191], v[238:241], v[66:69]
	v_mfma_f32_16x16x32_bf16 v[66:69], v[192:195], v[242:245], v[66:69]
	s_setprio 0
	s_mov_b32 m0, s1
	v_lshl_add_u64 v[148:149], v[148:149], 0, s[76:77]
	ds_read_b128 v[196:199], v151 offset:49152
	ds_read_b128 v[200:203], v151 offset:50176
	ds_read_b128 v[222:225], v151 offset:51200
	ds_read_b128 v[226:229], v151 offset:52224
	ds_read_b128 v[230:233], v151 offset:53248
	ds_read_b128 v[234:237], v151 offset:54272
	ds_read_b128 v[238:241], v151 offset:55296
	ds_read_b128 v[242:245], v151 offset:56320
	global_load_lds_dwordx4 v[148:149], off
	v_lshl_add_u64 v[148:149], v[168:169], 0, s[76:77]
	s_mov_b32 m0, s0
	s_nop 0
	global_load_lds_dwordx4 v[148:149], off
	v_lshl_add_u64 v[148:149], s[54:55], 0, v[136:137]
	s_mov_b32 m0, s47
	s_nop 0
	global_load_lds_dwordx4 v[148:149], off
	v_lshl_add_u64 v[148:149], s[54:55], 0, v[132:133]
	s_mov_b32 m0, s46
	s_nop 0
	global_load_lds_dwordx4 v[148:149], off
	v_lshl_add_u64 v[148:149], v[172:173], 0, s[76:77]
	s_mov_b32 m0, s83
	s_nop 0
	global_load_lds_dwordx4 v[148:149], off
	v_lshl_add_u64 v[148:149], v[212:213], 0, s[76:77]
	s_mov_b32 m0, s88
	s_nop 0
	global_load_lds_dwordx4 v[148:149], off
	s_waitcnt vmcnt(8)
	s_waitcnt lgkmcnt(0)
	s_setprio 1
	s_barrier
	v_mfma_f32_16x16x32_bf16 v[62:65], v[152:155], v[196:199], v[62:65]
	v_mfma_f32_16x16x32_bf16 v[62:65], v[156:159], v[200:203], v[62:65]
	v_mfma_f32_16x16x32_bf16 v[58:61], v[160:163], v[196:199], v[58:61]
	v_mfma_f32_16x16x32_bf16 v[58:61], v[164:167], v[200:203], v[58:61]
	v_mfma_f32_16x16x32_bf16 v[46:49], v[152:155], v[222:225], v[46:49]
	v_mfma_f32_16x16x32_bf16 v[46:49], v[156:159], v[226:229], v[46:49]
	v_mfma_f32_16x16x32_bf16 v[42:45], v[160:163], v[222:225], v[42:45]
	v_mfma_f32_16x16x32_bf16 v[42:45], v[164:167], v[226:229], v[42:45]
	v_mfma_f32_16x16x32_bf16 v[30:33], v[152:155], v[230:233], v[30:33]
	v_mfma_f32_16x16x32_bf16 v[30:33], v[156:159], v[234:237], v[30:33]
	v_mfma_f32_16x16x32_bf16 v[26:29], v[160:163], v[230:233], v[26:29]
	v_mfma_f32_16x16x32_bf16 v[26:29], v[164:167], v[234:237], v[26:29]
	v_mfma_f32_16x16x32_bf16 v[14:17], v[152:155], v[238:241], v[14:17]
	v_mfma_f32_16x16x32_bf16 v[14:17], v[156:159], v[242:245], v[14:17]
	v_mfma_f32_16x16x32_bf16 v[10:13], v[160:163], v[238:241], v[10:13]
	v_mfma_f32_16x16x32_bf16 v[10:13], v[164:167], v[242:245], v[10:13]
	s_setprio 0
	s_setprio 1
	v_mfma_f32_16x16x32_bf16 v[54:57], v[180:183], v[196:199], v[54:57]
	v_mfma_f32_16x16x32_bf16 v[54:57], v[184:187], v[200:203], v[54:57]
	v_mfma_f32_16x16x32_bf16 v[50:53], v[188:191], v[196:199], v[50:53]
	v_mfma_f32_16x16x32_bf16 v[50:53], v[192:195], v[200:203], v[50:53]
	v_mfma_f32_16x16x32_bf16 v[38:41], v[180:183], v[222:225], v[38:41]
	v_mfma_f32_16x16x32_bf16 v[38:41], v[184:187], v[226:229], v[38:41]
	v_mfma_f32_16x16x32_bf16 v[34:37], v[188:191], v[222:225], v[34:37]
	v_mfma_f32_16x16x32_bf16 v[34:37], v[192:195], v[226:229], v[34:37]
	v_mfma_f32_16x16x32_bf16 v[22:25], v[180:183], v[230:233], v[22:25]
	v_mfma_f32_16x16x32_bf16 v[22:25], v[184:187], v[234:237], v[22:25]
	v_mfma_f32_16x16x32_bf16 v[18:21], v[188:191], v[230:233], v[18:21]
	v_mfma_f32_16x16x32_bf16 v[18:21], v[192:195], v[234:237], v[18:21]
	v_mfma_f32_16x16x32_bf16 v[6:9], v[180:183], v[238:241], v[6:9]
	v_mfma_f32_16x16x32_bf16 v[6:9], v[184:187], v[242:245], v[6:9]
	s_setprio 2
	s_barrier
	v_mfma_f32_16x16x32_bf16 v[2:5], v[188:191], v[238:241], v[2:5]
	v_mfma_f32_16x16x32_bf16 v[2:5], v[192:195], v[242:245], v[2:5]
	s_setprio 0
	v_lshl_add_u64 v[144:145], v[144:145], 0, s[86:87]
	v_lshl_add_u64 v[146:147], v[146:147], 0, s[86:87]
	s_mov_b32 s29, s81

; #define PG8_STAGE(bufoff, gbase, voff) do { _Pragma("unroll") for (int _i = 0; _i < 2; ++_i) \
;         __builtin_amdgcn_global_load_lds((const unsigned*)((const char*)(gbase) + (voff)[_i]), (PG8_LAS unsigned*)(lds + (bufoff) + ldsw + _i * 8192), 16, 0, AUX_A); } while (0)
; #define PG8_STAGEB(bufoff, gbase, voff) do { _Pragma("unroll") for (int _i = 0; _i < 2; ++_i) \
;         __builtin_amdgcn_global_load_lds((const unsigned*)((const char*)(gbase) + (voff)[_i]), (PG8_LAS unsigned*)(lds + (bufoff) + ldsw + _i * 8192), 16, 0, AUX_B); } while (0)
; #define PG8_LDA(dst, b, h) do { _Pragma("unroll") for (int m = 0; m < 4; ++m) _Pragma("unroll") for (int k = 0; k < 2; ++k) dst[m][k] = *(const PG8_LAS bf16x8*)(lds + PG8_SA(b, h) + aoff + m * 2048 + k * 1024); } while (0)
; #define PG8_LDB(dst, b, h) do { _Pragma("unroll") for (int n = 0; n < 2; ++n) _Pragma("unroll") for (int k = 0; k < 2; ++k) dst[n][k] = *(const PG8_LAS bf16x8*)(lds + PG8_SB(b, h) + boff + n * 2048 + k * 1024); } while (0)
; #define PG8_WAIT_V(n) asm volatile("s_waitcnt vmcnt(" #n ")" ::: "memory")
; #define PG8_WAIT_L(n) asm volatile("s_waitcnt lgkmcnt(" #n ")" ::: "memory")
; #define PG8_BAR __builtin_amdgcn_s_barrier()
; template <class Epi, class Sched, bool ALIGN_EPI = false, bool SP2 = false>
; __device__ __forceinline__ void gemm_phase(PG8_LAS unsigned char* lds, const Gemm g, const Sched& S, const Epi& E) {
;     ...
;         for (int t = 0; t < nt; t += 2) {
;             const bool last = (t == nt - 2);
;             const char* a1 = PG8_KP(cA, t + 1, rot, nt);
;             const char* a2 = last ? nAr : PG8_KP(cA, t + 2, rot, nt); const char* b2 = last ? nBr : PG8_KP(cB, t + 2, rot, nt);
;             const char* a3 = a2 + kstep; const char* b3 = b2 + kstep;
;             if (last && has_next) S.a_ready(nxt);
;             if constexpr (SP2) {
;             PG8_LDB(B0, 0, 0); PG8_LDB(B1, 0, 1); PG8_SCHED; PG8_LDA(At, 0, 0); PG8_STAGE(PG8_SA(1, 1), a1 + hstep, voffA);
;             PG8_WAIT_V(8); PG8_WAIT_L(0); PG8_BAR; PG8_MMA(0, 0, At, B0); PG8_MMA(0, 1, At, B1); PG8_BAR; PG8_SCHED;
;             PG8_LDA(At, 0, 1); PG8_STAGEB(PG8_SB(0, 0), b2, voffB); PG8_STAGEB(PG8_SB(0, 1), b2 + hstep, voffB); PG8_STAGE(PG8_SA(0, 0), a2, voffA);
;             PG8_WAIT_V(8); PG8_WAIT_L(0); PG8_BAR; PG8_MMA(1, 0, At, B0); PG8_MMA(1, 1, At, B1); PG8_BAR; PG8_SCHED;
.Lrp_1157:
.Lpk_1157:
	s_add_i32 s81, s29, 2
	s_cmp_lt_u32 s29, 14
	s_cselect_b32 s0, 0, -16
	s_add_i32 s0, s81, s0
	s_ashr_i32 s1, s0, 31
	s_lshl_b64 s[0:1], s[0:1], 7
	s_add_u32 s2, s52, s0
	s_addc_u32 s46, s53, s1
	s_add_u32 s0, s50, s0
	s_addc_u32 s1, s51, s1
	s_cmp_eq_u32 s29, 14
	s_cselect_b32 s59, s19, s46
	s_cselect_b32 s58, s39, s2
	s_cselect_b32 s61, s92, s1
	s_cselect_b32 s60, s93, s0
	s_add_i32 s2, 0, 0x10000
	s_add_i32 s94, s2, s70
	s_add_i32 s46, 0, 0x14000
	s_add_i32 m0, s71, 0xc000
	s_add_i32 s84, s71, 0xe000
	s_add_i32 s95, s94, 0x2000
	s_add_u32 s62, s60, 0x40000
	s_addc_u32 s63, s61, 0
	s_add_i32 s96, s46, s70
	s_add_i32 s97, s96, 0x2000
	s_add_i32 vcc_lo, 0, 0x18000
	s_add_i32 vcc_hi, 0, 0x1c000
	s_add_u32 s56, s58, 0x40000
	s_addc_u32 s57, s59, 0
	s_add_i32 s1, vcc_lo, s70
	s_add_i32 s0, s1, 0x2000
	s_add_u32 s54, s60, 0x40080
	s_addc_u32 s55, s61, 0
	s_add_i32 s47, vcc_hi, s70
	s_add_i32 s46, s47, 0x2000
	global_load_lds_dwordx4 v[146:147], off
	s_mov_b32 m0, s84
	s_nop 0
	global_load_lds_dwordx4 v[144:145], off
	s_waitcnt vmcnt(8)
	s_waitcnt lgkmcnt(0)
	s_setprio 1
	s_barrier
	v_mfma_f32_16x16x32_bf16 v[128:131], v[148:151], v[196:199], 0
	v_mfma_f32_16x16x32_bf16 v[128:131], v[154:157], v[200:203], v[128:131]
	v_mfma_f32_16x16x32_bf16 v[124:127], v[158:161], v[196:199], 0
	v_mfma_f32_16x16x32_bf16 v[124:127], v[162:165], v[200:203], v[124:127]
	v_mfma_f32_16x16x32_bf16 v[112:115], v[148:151], v[222:225], 0
	v_mfma_f32_16x16x32_bf16 v[112:115], v[154:157], v[226:229], v[112:115]
	v_mfma_f32_16x16x32_bf16 v[108:111], v[158:161], v[222:225], 0
	v_mfma_f32_16x16x32_bf16 v[108:111], v[162:165], v[226:229], v[108:111]
	v_mfma_f32_16x16x32_bf16 v[94:97], v[148:151], v[230:233], 0
	v_mfma_f32_16x16x32_bf16 v[94:97], v[154:157], v[234:237], v[94:97]
	v_mfma_f32_16x16x32_bf16 v[90:93], v[158:161], v[230:233], 0
	v_mfma_f32_16x16x32_bf16 v[90:93], v[162:165], v[234:237], v[90:93]
	v_mfma_f32_16x16x32_bf16 v[78:81], v[148:151], v[238:241], 0
	v_mfma_f32_16x16x32_bf16 v[78:81], v[154:157], v[242:245], v[78:81]
	v_mfma_f32_16x16x32_bf16 v[74:77], v[158:161], v[238:241], 0
	v_mfma_f32_16x16x32_bf16 v[74:77], v[162:165], v[242:245], v[74:77]
	s_setprio 0
	s_setprio 1
	v_mfma_f32_16x16x32_bf16 v[120:123], v[180:183], v[196:199], 0
	v_mfma_f32_16x16x32_bf16 v[120:123], v[184:187], v[200:203], v[120:123]
	v_mfma_f32_16x16x32_bf16 v[116:119], v[188:191], v[196:199], 0
	v_mfma_f32_16x16x32_bf16 v[116:119], v[192:195], v[200:203], v[116:119]
	v_mfma_f32_16x16x32_bf16 v[104:107], v[180:183], v[222:225], 0
	v_mfma_f32_16x16x32_bf16 v[104:107], v[184:187], v[226:229], v[104:107]
	v_mfma_f32_16x16x32_bf16 v[100:103], v[188:191], v[222:225], 0
	v_mfma_f32_16x16x32_bf16 v[100:103], v[192:195], v[226:229], v[100:103]
	v_mfma_f32_16x16x32_bf16 v[86:89], v[180:183], v[230:233], 0
	v_mfma_f32_16x16x32_bf16 v[86:89], v[184:187], v[234:237], v[86:89]
	v_mfma_f32_16x16x32_bf16 v[82:85], v[188:191], v[230:233], 0
	v_mfma_f32_16x16x32_bf16 v[82:85], v[192:195], v[234:237], v[82:85]
	v_mfma_f32_16x16x32_bf16 v[70:73], v[180:183], v[238:241], 0
	v_mfma_f32_16x16x32_bf16 v[70:73], v[184:187], v[242:245], v[70:73]
	s_setprio 2
	s_barrier
	v_mfma_f32_16x16x32_bf16 v[66:69], v[188:191], v[238:241], 0
	v_mfma_f32_16x16x32_bf16 v[66:69], v[192:195], v[242:245], v[66:69]
	s_setprio 0
	s_mov_b32 m0, s94
	v_lshl_add_u64 v[166:167], s[60:61], 0, v[136:137]
	ds_read_b128 v[196:199], v153 offset:16384
	ds_read_b128 v[200:203], v153 offset:17408
	ds_read_b128 v[222:225], v153 offset:18432
	ds_read_b128 v[226:229], v153 offset:19456
	ds_read_b128 v[230:233], v153 offset:20480
	ds_read_b128 v[234:237], v153 offset:21504
	ds_read_b128 v[238:241], v153 offset:22528
	ds_read_b128 v[242:245], v153 offset:23552
	global_load_lds_dwordx4 v[166:167], off
	v_lshl_add_u64 v[168:169], s[60:61], 0, v[132:133]
	s_mov_b32 m0, s95
	v_lshl_add_u64 v[172:173], s[62:63], 0, v[136:137]
	global_load_lds_dwordx4 v[168:169], off
	s_mov_b32 m0, s96
	v_lshl_add_u64 v[212:213], s[58:59], 0, v[134:135]
	global_load_lds_dwordx4 v[172:173], off
	v_lshl_add_u64 v[172:173], s[62:63], 0, v[132:133]
	s_mov_b32 m0, s97
	s_nop 0
	global_load_lds_dwordx4 v[172:173], off
	v_lshl_add_u64 v[172:173], s[58:59], 0, v[138:139]
	s_mov_b32 m0, s71
	s_nop 0
	global_load_lds_dwordx4 v[172:173], off
	s_mov_b32 m0, s75
	s_nop 0
	global_load_lds_dwordx4 v[212:213], off
	s_waitcnt vmcnt(8)
	s_waitcnt lgkmcnt(0)
	s_setprio 1
	s_barrier
	v_mfma_f32_16x16x32_bf16 v[62:65], v[148:151], v[196:199], 0
	v_mfma_f32_16x16x32_bf16 v[62:65], v[154:157], v[200:203], v[62:65]
	v_mfma_f32_16x16x32_bf16 v[58:61], v[158:161], v[196:199], 0
	v_mfma_f32_16x16x32_bf16 v[58:61], v[162:165], v[200:203], v[58:61]
	v_mfma_f32_16x16x32_bf16 v[46:49], v[148:151], v[222:225], 0
	v_mfma_f32_16x16x32_bf16 v[46:49], v[154:157], v[226:229], v[46:49]
	v_mfma_f32_16x16x32_bf16 v[42:45], v[158:161], v[222:225], 0
	v_mfma_f32_16x16x32_bf16 v[42:45], v[162:165], v[226:229], v[42:45]
	v_mfma_f32_16x16x32_bf16 v[30:33], v[148:151], v[230:233], 0
	v_mfma_f32_16x16x32_bf16 v[30:33], v[154:157], v[234:237], v[30:33]
	v_mfma_f32_16x16x32_bf16 v[26:29], v[158:161], v[230:233], 0
	v_mfma_f32_16x16x32_bf16 v[26:29], v[162:165], v[234:237], v[26:29]
	v_mfma_f32_16x16x32_bf16 v[14:17], v[148:151], v[238:241], 0
	v_mfma_f32_16x16x32_bf16 v[14:17], v[154:157], v[242:245], v[14:17]
	v_mfma_f32_16x16x32_bf16 v[10:13], v[158:161], v[238:241], 0
	v_mfma_f32_16x16x32_bf16 v[10:13], v[162:165], v[242:245], v[10:13]
	s_setprio 0
	s_setprio 1
	v_mfma_f32_16x16x32_bf16 v[54:57], v[180:183], v[196:199], 0
	v_mfma_f32_16x16x32_bf16 v[54:57], v[184:187], v[200:203], v[54:57]
	v_mfma_f32_16x16x32_bf16 v[50:53], v[188:191], v[196:199], 0
	v_mfma_f32_16x16x32_bf16 v[50:53], v[192:195], v[200:203], v[50:53]
	v_mfma_f32_16x16x32_bf16 v[38:41], v[180:183], v[222:225], 0
	v_mfma_f32_16x16x32_bf16 v[38:41], v[184:187], v[226:229], v[38:41]
	v_mfma_f32_16x16x32_bf16 v[34:37], v[188:191], v[222:225], 0
	v_mfma_f32_16x16x32_bf16 v[34:37], v[192:195], v[226:229], v[34:37]
	v_mfma_f32_16x16x32_bf16 v[22:25], v[180:183], v[230:233], 0
	v_mfma_f32_16x16x32_bf16 v[22:25], v[184:187], v[234:237], v[22:25]
	v_mfma_f32_16x16x32_bf16 v[18:21], v[188:191], v[230:233], 0
	v_mfma_f32_16x16x32_bf16 v[18:21], v[192:195], v[234:237], v[18:21]
	v_mfma_f32_16x16x32_bf16 v[6:9], v[180:183], v[238:241], 0
	v_mfma_f32_16x16x32_bf16 v[6:9], v[184:187], v[242:245], v[6:9]
	s_setprio 2
	s_barrier
; #define PG8_STAGE(bufoff, gbase, voff) do { _Pragma("unroll") for (int _i = 0; _i < 2; ++_i) \
;         __builtin_amdgcn_global_load_lds((const unsigned*)((const char*)(gbase) + (voff)[_i]), (PG8_LAS unsigned*)(lds + (bufoff) + ldsw + _i * 8192), 16, 0, AUX_A); } while (0)
; #define PG8_STAGEB(bufoff, gbase, voff) do { _Pragma("unroll") for (int _i = 0; _i < 2; ++_i) \
;         __builtin_amdgcn_global_load_lds((const unsigned*)((const char*)(gbase) + (voff)[_i]), (PG8_LAS unsigned*)(lds + (bufoff) + ldsw + _i * 8192), 16, 0, AUX_B); } while (0)
; #define PG8_LDA(dst, b, h) do { _Pragma("unroll") for (int m = 0; m < 4; ++m) _Pragma("unroll") for (int k = 0; k < 2; ++k) dst[m][k] = *(const PG8_LAS bf16x8*)(lds + PG8_SA(b, h) + aoff + m * 2048 + k * 1024); } while (0)
; #define PG8_LDB(dst, b, h) do { _Pragma("unroll") for (int n = 0; n < 2; ++n) _Pragma("unroll") for (int k = 0; k < 2; ++k) dst[n][k] = *(const PG8_LAS bf16x8*)(lds + PG8_SB(b, h) + boff + n * 2048 + k * 1024); } while (0)
; #define PG8_MMA(ai, bj, At, Bt) do { __builtin_amdgcn_s_setprio(1); _Pragma("unroll") for (int m = 0; m < 4; ++m) _Pragma("unroll") for (int n = 0; n < 2; ++n) _Pragma("unroll") for (int k = 0; k < 2; ++k) \
;         acc[ai][bj][m][n] = __builtin_amdgcn_mfma_f32_16x16x32_bf16(Bt[n][k], At[m][k], acc[ai][bj][m][n], 0, 0, 0); __builtin_amdgcn_s_setprio(0); } while (0)
; #define PG8_WAIT_V(n) asm volatile("s_waitcnt vmcnt(" #n ")" ::: "memory")
; #define PG8_WAIT_L(n) asm volatile("s_waitcnt lgkmcnt(" #n ")" ::: "memory")
; #define PG8_BAR __builtin_amdgcn_s_barrier()
; #define PG8_SCHED __builtin_amdgcn_sched_barrier(0)
; template <class Epi, class Sched, bool ALIGN_EPI = false, bool SP2 = false>
; __device__ __forceinline__ void gemm_phase(PG8_LAS unsigned char* lds, const Gemm g, const Sched& S, const Epi& E) {
;     ...
;         for (int t = 0; t < nt; t += 2) {
;     ...
;             PG8_LDB(B0, 1, 0); PG8_LDB(B1, 1, 1); PG8_SCHED; PG8_LDA(At, 1, 0); PG8_STAGE(PG8_SA(0, 1), a2 + hstep, voffA);
;             PG8_WAIT_V(8); PG8_WAIT_L(0); PG8_BAR; PG8_MMA(0, 0, At, B0); PG8_MMA(0, 1, At, B1); PG8_BAR; PG8_SCHED;
;             PG8_LDA(At, 1, 1); PG8_STAGEB(PG8_SB(1, 0), b3, voffB); PG8_STAGEB(PG8_SB(1, 1), b3 + hstep, voffB); PG8_STAGE(PG8_SA(1, 0), a3, voffA);
;             PG8_WAIT_V(8); PG8_WAIT_L(0); PG8_BAR; PG8_MMA(1, 0, At, B0); PG8_MMA(1, 1, At, B1); PG8_BAR; PG8_SCHED;
	v_mfma_f32_16x16x32_bf16 v[2:5], v[188:191], v[238:241], 0
	v_mfma_f32_16x16x32_bf16 v[2:5], v[192:195], v[242:245], v[2:5]
	s_setprio 0
	v_add_u32_e32 v162, vcc_lo, v99
	v_add_u32_e32 v192, vcc_hi, v99
	ds_read_b128 v[148:151], v162
	ds_read_b128 v[154:157], v162 offset:1024
	ds_read_b128 v[158:161], v162 offset:2048
	ds_read_b128 v[162:165], v162 offset:3072
	ds_read_b128 v[180:183], v192
	ds_read_b128 v[184:187], v192 offset:1024
	ds_read_b128 v[188:191], v192 offset:2048
	ds_read_b128 v[192:195], v192 offset:3072
	s_mov_b32 m0, s78
	v_lshl_add_u64 v[246:247], s[56:57], 0, v[138:139]
	ds_read_b128 v[196:199], v153 offset:32768
	ds_read_b128 v[200:203], v153 offset:33792
	ds_read_b128 v[222:225], v153 offset:34816
	ds_read_b128 v[226:229], v153 offset:35840
	ds_read_b128 v[230:233], v153 offset:36864
	ds_read_b128 v[234:237], v153 offset:37888
	ds_read_b128 v[238:241], v153 offset:38912
	ds_read_b128 v[242:245], v153 offset:39936
	global_load_lds_dwordx4 v[246:247], off
	v_lshl_add_u64 v[246:247], s[56:57], 0, v[134:135]
	s_mov_b32 m0, s82
	s_nop 0
	global_load_lds_dwordx4 v[246:247], off
	s_waitcnt vmcnt(8)
	s_waitcnt lgkmcnt(0)
	s_setprio 1
	s_barrier
	v_mfma_f32_16x16x32_bf16 v[128:131], v[148:151], v[196:199], v[128:131]
	v_mfma_f32_16x16x32_bf16 v[128:131], v[154:157], v[200:203], v[128:131]
	v_mfma_f32_16x16x32_bf16 v[124:127], v[158:161], v[196:199], v[124:127]
	v_mfma_f32_16x16x32_bf16 v[124:127], v[162:165], v[200:203], v[124:127]
	v_mfma_f32_16x16x32_bf16 v[112:115], v[148:151], v[222:225], v[112:115]
	v_mfma_f32_16x16x32_bf16 v[112:115], v[154:157], v[226:229], v[112:115]
	v_mfma_f32_16x16x32_bf16 v[108:111], v[158:161], v[222:225], v[108:111]
	v_mfma_f32_16x16x32_bf16 v[108:111], v[162:165], v[226:229], v[108:111]
	v_mfma_f32_16x16x32_bf16 v[94:97], v[148:151], v[230:233], v[94:97]
	v_mfma_f32_16x16x32_bf16 v[94:97], v[154:157], v[234:237], v[94:97]
	v_mfma_f32_16x16x32_bf16 v[90:93], v[158:161], v[230:233], v[90:93]
	v_mfma_f32_16x16x32_bf16 v[90:93], v[162:165], v[234:237], v[90:93]
	v_mfma_f32_16x16x32_bf16 v[78:81], v[148:151], v[238:241], v[78:81]
	v_mfma_f32_16x16x32_bf16 v[78:81], v[154:157], v[242:245], v[78:81]
	v_mfma_f32_16x16x32_bf16 v[74:77], v[158:161], v[238:241], v[74:77]
	v_mfma_f32_16x16x32_bf16 v[74:77], v[162:165], v[242:245], v[74:77]
	s_setprio 0
	s_setprio 1
	v_mfma_f32_16x16x32_bf16 v[120:123], v[180:183], v[196:199], v[120:123]
	v_mfma_f32_16x16x32_bf16 v[120:123], v[184:187], v[200:203], v[120:123]
	v_mfma_f32_16x16x32_bf16 v[116:119], v[188:191], v[196:199], v[116:119]
	v_mfma_f32_16x16x32_bf16 v[116:119], v[192:195], v[200:203], v[116:119]
	v_mfma_f32_16x16x32_bf16 v[104:107], v[180:183], v[222:225], v[104:107]
	v_mfma_f32_16x16x32_bf16 v[104:107], v[184:187], v[226:229], v[104:107]
	v_mfma_f32_16x16x32_bf16 v[100:103], v[188:191], v[222:225], v[100:103]
	v_mfma_f32_16x16x32_bf16 v[100:103], v[192:195], v[226:229], v[100:103]
	v_mfma_f32_16x16x32_bf16 v[86:89], v[180:183], v[230:233], v[86:89]
	v_mfma_f32_16x16x32_bf16 v[86:89], v[184:187], v[234:237], v[86:89]
	v_mfma_f32_16x16x32_bf16 v[82:85], v[188:191], v[230:233], v[82:85]
	v_mfma_f32_16x16x32_bf16 v[82:85], v[192:195], v[234:237], v[82:85]
	v_mfma_f32_16x16x32_bf16 v[70:73], v[180:183], v[238:241], v[70:73]
	v_mfma_f32_16x16x32_bf16 v[70:73], v[184:187], v[242:245], v[70:73]
	s_setprio 2
	s_barrier
	v_mfma_f32_16x16x32_bf16 v[66:69], v[188:191], v[238:241], v[66:69]
	v_mfma_f32_16x16x32_bf16 v[66:69], v[192:195], v[242:245], v[66:69]
	s_setprio 0
	s_mov_b32 m0, s1
	v_lshl_add_u64 v[166:167], v[166:167], 0, s[76:77]
	ds_read_b128 v[196:199], v153 offset:49152
	ds_read_b128 v[200:203], v153 offset:50176
	ds_read_b128 v[222:225], v153 offset:51200
	ds_read_b128 v[226:229], v153 offset:52224
	ds_read_b128 v[230:233], v153 offset:53248
	ds_read_b128 v[234:237], v153 offset:54272
	ds_read_b128 v[238:241], v153 offset:55296
	ds_read_b128 v[242:245], v153 offset:56320
	global_load_lds_dwordx4 v[166:167], off
	v_lshl_add_u64 v[166:167], v[168:169], 0, s[76:77]
	s_mov_b32 m0, s0
	s_nop 0
	global_load_lds_dwordx4 v[166:167], off
	v_lshl_add_u64 v[166:167], s[54:55], 0, v[136:137]
	s_mov_b32 m0, s47
	s_nop 0
	global_load_lds_dwordx4 v[166:167], off
	v_lshl_add_u64 v[166:167], s[54:55], 0, v[132:133]
	s_mov_b32 m0, s46
	s_nop 0
	global_load_lds_dwordx4 v[166:167], off
	v_lshl_add_u64 v[166:167], v[172:173], 0, s[76:77]
	s_mov_b32 m0, s83
	s_nop 0
	global_load_lds_dwordx4 v[166:167], off
	v_lshl_add_u64 v[166:167], v[212:213], 0, s[76:77]
	s_mov_b32 m0, s88
	s_nop 0
	global_load_lds_dwordx4 v[166:167], off
	s_waitcnt vmcnt(8)
	s_waitcnt lgkmcnt(0)
	s_setprio 1
	s_barrier
	v_mfma_f32_16x16x32_bf16 v[62:65], v[148:151], v[196:199], v[62:65]
	v_mfma_f32_16x16x32_bf16 v[62:65], v[154:157], v[200:203], v[62:65]
	v_mfma_f32_16x16x32_bf16 v[58:61], v[158:161], v[196:199], v[58:61]
	v_mfma_f32_16x16x32_bf16 v[58:61], v[162:165], v[200:203], v[58:61]
	v_mfma_f32_16x16x32_bf16 v[46:49], v[148:151], v[222:225], v[46:49]
	v_mfma_f32_16x16x32_bf16 v[46:49], v[154:157], v[226:229], v[46:49]
	v_mfma_f32_16x16x32_bf16 v[42:45], v[158:161], v[222:225], v[42:45]
	v_mfma_f32_16x16x32_bf16 v[42:45], v[162:165], v[226:229], v[42:45]
	v_mfma_f32_16x16x32_bf16 v[30:33], v[148:151], v[230:233], v[30:33]
	v_mfma_f32_16x16x32_bf16 v[30:33], v[154:157], v[234:237], v[30:33]
	v_mfma_f32_16x16x32_bf16 v[26:29], v[158:161], v[230:233], v[26:29]
	v_mfma_f32_16x16x32_bf16 v[26:29], v[162:165], v[234:237], v[26:29]
	v_mfma_f32_16x16x32_bf16 v[14:17], v[148:151], v[238:241], v[14:17]
	v_mfma_f32_16x16x32_bf16 v[14:17], v[154:157], v[242:245], v[14:17]
	v_mfma_f32_16x16x32_bf16 v[10:13], v[158:161], v[238:241], v[10:13]
	v_mfma_f32_16x16x32_bf16 v[10:13], v[162:165], v[242:245], v[10:13]
	s_setprio 0
	s_setprio 1
	v_mfma_f32_16x16x32_bf16 v[54:57], v[180:183], v[196:199], v[54:57]
	v_mfma_f32_16x16x32_bf16 v[54:57], v[184:187], v[200:203], v[54:57]
	v_mfma_f32_16x16x32_bf16 v[50:53], v[188:191], v[196:199], v[50:53]
	v_mfma_f32_16x16x32_bf16 v[50:53], v[192:195], v[200:203], v[50:53]
	v_mfma_f32_16x16x32_bf16 v[38:41], v[180:183], v[222:225], v[38:41]
	v_mfma_f32_16x16x32_bf16 v[38:41], v[184:187], v[226:229], v[38:41]
	v_mfma_f32_16x16x32_bf16 v[34:37], v[188:191], v[222:225], v[34:37]
	v_mfma_f32_16x16x32_bf16 v[34:37], v[192:195], v[226:229], v[34:37]
	v_mfma_f32_16x16x32_bf16 v[22:25], v[180:183], v[230:233], v[22:25]
	v_mfma_f32_16x16x32_bf16 v[22:25], v[184:187], v[234:237], v[22:25]
	v_mfma_f32_16x16x32_bf16 v[18:21], v[188:191], v[230:233], v[18:21]
	v_mfma_f32_16x16x32_bf16 v[18:21], v[192:195], v[234:237], v[18:21]
	v_mfma_f32_16x16x32_bf16 v[6:9], v[180:183], v[238:241], v[6:9]
	v_mfma_f32_16x16x32_bf16 v[6:9], v[184:187], v[242:245], v[6:9]
	s_setprio 2
	s_barrier
	v_mfma_f32_16x16x32_bf16 v[2:5], v[188:191], v[238:241], v[2:5]
	v_mfma_f32_16x16x32_bf16 v[2:5], v[192:195], v[242:245], v[2:5]
	s_setprio 0
	v_lshl_add_u64 v[144:145], v[144:145], 0, s[86:87]
	v_lshl_add_u64 v[146:147], v[146:147], 0, s[86:87]
	s_mov_b32 s29, s81
